# one static s_setprio 1 for waves 4-7 at kernel entry; all 80 per-block priority toggles in the GEMM K-loops removed
# speedup vs baseline: 1.0021x; 1.0004x over previous
_Z8yoco_fwd4Args:
	v_lshl_add_u32 v1, v0, 2, 0
	v_writelane_b32 v255, s0, 0
	v_add_u32_e32 v1, 0x20000, v1
	v_mov_b32_e32 v2, 0
	s_mov_b32 s97, s2
	v_writelane_b32 v255, s1, 1
	v_readfirstlane_b32 s3, v0
	s_cmpk_lt_u32 s3, 0x100
	s_cbranch_scc1 .Lprio_lo
	s_setprio 1
.Lprio_lo:
	ds_write2st64_b32 v1, v2, v2 offset1:8
	ds_write2st64_b32 v1, v2, v2 offset0:16 offset1:24
	v_or_b32_e32 v1, 0x800, v0
	s_mov_b64 s[4:5], -1
	s_and_saveexec_b64 s[6:7], s[4:5]
	v_lshl_add_u32 v3, v1, 2, 0
	v_add_u32_e32 v3, 0x20000, v3
	ds_write_b32 v3, v2
	s_or_b64 exec, exec, s[6:7]
	s_and_saveexec_b64 s[6:7], s[4:5]
	s_add_i32 s0, 0, 0x20000
	v_lshl_add_u32 v1, v1, 2, s0
	v_mov_b32_e32 v2, 0
	ds_write_b32 v1, v2 offset:2048
	s_or_b64 exec, exec, s[6:7]
	v_or_b32_e32 v1, 0xc00, v0
	v_cmp_gt_u32_e64 s[4:5], 7, 6
	v_cmp_gt_u32_e64 s[0:1], 7, 5
	s_and_saveexec_b64 s[6:7], s[0:1]
	v_lshl_add_u32 v2, v1, 2, 0
	v_add_u32_e32 v2, 0x20000, v2
	v_mov_b32_e32 v3, 0
	ds_write_b32 v2, v3
	s_or_b64 exec, exec, s[6:7]
	s_and_saveexec_b64 s[6:7], s[4:5]
	s_add_i32 s0, 0, 0x20000
	v_lshl_add_u32 v1, v1, 2, s0
	v_mov_b32_e32 v2, 0
	ds_write_b32 v1, v2 offset:2048
	s_or_b64 exec, exec, s[6:7]
	v_readlane_b32 s6, v255, 0
	v_readlane_b32 s7, v255, 1
	s_mov_b64 s[0:1], s[6:7]
	s_waitcnt lgkmcnt(0)
	s_barrier
	v_mbcnt_lo_u32_b32 v1, -1, 0
	v_mbcnt_hi_u32_b32 v1, -1, v1
	s_load_dword s2, s[6:7], 0x118
	s_mov_b32 s4, s97
	s_waitcnt lgkmcnt(0)
	v_writelane_b32 v255, s2, 2
	s_load_dwordx2 s[4:5], s[0:1], 0xc0
	s_load_dwordx2 s[8:9], s[0:1], 0x110
	s_add_u32 s0, s6, 0x118
	s_addc_u32 s1, s7, 0
	v_writelane_b32 v255, s0, 3
	s_nop 1
	v_writelane_b32 v255, s1, 4
	s_waitcnt lgkmcnt(0)
	s_add_u32 s0, s4, 0x4000
	s_addc_u32 s1, s5, 0
	v_writelane_b32 v255, s0, 5
	s_nop 1
	v_writelane_b32 v255, s1, 6
	v_writelane_b32 v255, s8, 7
	s_sub_i32 s0, s9, s8
	s_mov_b32 s1, 0
	v_writelane_b32 v255, s9, 8
	v_writelane_b32 v255, s1, 9
	s_cmp_lt_i32 s0, 2
	s_mov_b32 s0, 0
	v_writelane_b32 v255, s0, 10
	s_cbranch_scc1 .LBB0_16
	s_getreg_b32 s0, hwreg(HW_REG_XCC_ID, 0, 4)
	s_and_b32 s0, s0, 15
	v_cmp_eq_u32_e32 vcc, 0, v0
	v_writelane_b32 v255, s0, 9
	s_and_saveexec_b64 s[6:7], vcc
	s_cbranch_execz .LBB0_15
	s_mov_b64 s[10:11], exec
	v_mbcnt_lo_u32_b32 v0, s10, 0
	v_mbcnt_hi_u32_b32 v0, s11, v0
	v_cmp_eq_u32_e32 vcc, 0, v0
	s_and_saveexec_b64 s[8:9], vcc
	s_cbranch_execz .LBB0_12
	v_readlane_b32 s0, v255, 9
	s_lshl_b32 s0, s0, 8
	s_bcnt1_i32_b64 s1, s[10:11]
	v_mov_b32_e32 v0, s0
	v_mov_b32_e32 v1, s1
	v_readlane_b32 s0, v255, 5
	v_readlane_b32 s1, v255, 6
	s_nop 4
	global_atomic_add v0, v1, s[0:1] offset:1024

.LBB0_245:
	s_waitcnt lgkmcnt(0)
	s_barrier
	s_waitcnt lgkmcnt(0)
	v_mfma_f32_16x16x32_bf16 v[82:85], v[166:169], v[190:193], v[82:85]
	v_mfma_f32_16x16x32_bf16 v[78:81], v[174:177], v[190:193], v[78:81]
	v_mfma_f32_16x16x32_bf16 v[50:53], v[166:169], v[182:185], v[50:53]
	v_mfma_f32_16x16x32_bf16 v[46:49], v[174:177], v[182:185], v[46:49]
	v_mfma_f32_16x16x32_bf16 v[34:37], v[166:169], v[62:65], v[34:37]
	v_mfma_f32_16x16x32_bf16 v[30:33], v[174:177], v[62:65], v[30:33]
	v_mfma_f32_16x16x32_bf16 v[18:21], v[166:169], v[54:57], v[18:21]
	v_mfma_f32_16x16x32_bf16 v[10:13], v[174:177], v[54:57], v[10:13]
	v_mfma_f32_16x16x32_bf16 v[82:85], v[170:173], v[194:197], v[82:85]
	v_mfma_f32_16x16x32_bf16 v[78:81], v[178:181], v[194:197], v[78:81]
	v_mfma_f32_16x16x32_bf16 v[50:53], v[170:173], v[186:189], v[50:53]
	v_mfma_f32_16x16x32_bf16 v[46:49], v[178:181], v[186:189], v[46:49]
	v_mfma_f32_16x16x32_bf16 v[34:37], v[170:173], v[66:69], v[34:37]
	v_mfma_f32_16x16x32_bf16 v[30:33], v[178:181], v[66:69], v[30:33]
	v_mfma_f32_16x16x32_bf16 v[18:21], v[170:173], v[58:61], v[18:21]
	v_mfma_f32_16x16x32_bf16 v[10:13], v[178:181], v[58:61], v[10:13]
	v_mfma_f32_16x16x32_bf16 v[74:77], v[150:153], v[190:193], v[74:77]
	v_mfma_f32_16x16x32_bf16 v[70:73], v[158:161], v[190:193], v[70:73]
	v_mfma_f32_16x16x32_bf16 v[42:45], v[150:153], v[182:185], v[42:45]
	v_mfma_f32_16x16x32_bf16 v[38:41], v[158:161], v[182:185], v[38:41]
	v_mfma_f32_16x16x32_bf16 v[26:29], v[150:153], v[62:65], v[26:29]
	v_mfma_f32_16x16x32_bf16 v[22:25], v[158:161], v[62:65], v[22:25]
	v_mfma_f32_16x16x32_bf16 v[6:9], v[150:153], v[54:57], v[6:9]
	v_mfma_f32_16x16x32_bf16 v[2:5], v[158:161], v[54:57], v[2:5]
	v_mfma_f32_16x16x32_bf16 v[74:77], v[154:157], v[194:197], v[74:77]
	v_mfma_f32_16x16x32_bf16 v[70:73], v[162:165], v[194:197], v[70:73]
	v_mfma_f32_16x16x32_bf16 v[42:45], v[154:157], v[186:189], v[42:45]
	v_mfma_f32_16x16x32_bf16 v[38:41], v[162:165], v[186:189], v[38:41]
	v_mfma_f32_16x16x32_bf16 v[26:29], v[154:157], v[66:69], v[26:29]
	v_mfma_f32_16x16x32_bf16 v[22:25], v[162:165], v[66:69], v[22:25]
	v_mfma_f32_16x16x32_bf16 v[6:9], v[154:157], v[58:61], v[6:9]
	v_mfma_f32_16x16x32_bf16 v[2:5], v[162:165], v[58:61], v[2:5]
	s_barrier
	s_add_i32 s65, s65, 2
	s_add_u32 s8, s8, 0x100
	s_addc_u32 s9, s9, 0
	s_add_u32 s33, s33, 0x100
	s_addc_u32 s64, s64, 0
	s_cmp_gt_u32 s65, 29
	s_cbranch_scc1 .LBB0_256
.LBB0_246:
	ds_read_b128 v[166:169], v236
	ds_read_b128 v[170:173], v236 offset:1024
	ds_read_b128 v[174:177], v236 offset:2048
	ds_read_b128 v[178:181], v236 offset:3072
	ds_read_b128 v[150:153], v237
	ds_read_b128 v[154:157], v237 offset:1024
	ds_read_b128 v[158:161], v237 offset:2048
	ds_read_b128 v[162:165], v237 offset:3072
	s_add_u32 s88, s8, 0xfff80080
	s_addc_u32 s89, s9, -1
	s_cmp_lg_u32 s65, 28
	s_cselect_b64 s[90:91], -1, 0
	s_and_b64 s[86:87], s[90:91], exec
	s_cselect_b32 s87, s64, s77
	s_cselect_b32 s86, s33, s79
	s_cselect_b32 s89, s89, s5
	s_cselect_b32 s88, s88, s7
	v_lshl_add_u64 v[54:55], s[8:9], 0, v[222:223]
	s_add_i32 m0, s29, 0xc000
	ds_read_b128 v[182:185], v245
	ds_read_b128 v[186:189], v245 offset:1024
	ds_read_b128 v[190:193], v245 offset:2048
	ds_read_b128 v[194:197], v245 offset:3072
	ds_read_b128 v[198:201], v245 offset:4096
	ds_read_b128 v[202:205], v245 offset:5120
	ds_read_b128 v[206:209], v245 offset:6144
	ds_read_b128 v[210:213], v245 offset:7168
	global_load_lds_dwordx4 v[54:55], off
	v_lshl_add_u64 v[54:55], s[8:9], 0, v[224:225]
	s_add_i32 m0, s29, 0xe000
	s_nop 0
	global_load_lds_dwordx4 v[54:55], off
	s_waitcnt vmcnt(8)
	s_waitcnt lgkmcnt(0)
	s_barrier
	s_waitcnt lgkmcnt(0)
	v_mfma_f32_16x16x32_bf16 v[54:57], v[166:169], v[182:185], v[146:149]
	v_mfma_f32_16x16x32_bf16 v[58:61], v[174:177], v[182:185], v[142:145]
	v_mfma_f32_16x16x32_bf16 v[62:65], v[166:169], v[190:193], v[130:133]
	v_mfma_f32_16x16x32_bf16 v[66:69], v[174:177], v[190:193], v[126:129]
	v_mfma_f32_16x16x32_bf16 v[114:117], v[166:169], v[198:201], v[114:117]
	v_mfma_f32_16x16x32_bf16 v[110:113], v[174:177], v[198:201], v[110:113]
	v_mfma_f32_16x16x32_bf16 v[98:101], v[166:169], v[206:209], v[98:101]
	v_mfma_f32_16x16x32_bf16 v[94:97], v[174:177], v[206:209], v[94:97]
	v_mfma_f32_16x16x32_bf16 v[54:57], v[170:173], v[186:189], v[54:57]
	v_mfma_f32_16x16x32_bf16 v[58:61], v[178:181], v[186:189], v[58:61]
	v_mfma_f32_16x16x32_bf16 v[62:65], v[170:173], v[194:197], v[62:65]
	v_mfma_f32_16x16x32_bf16 v[66:69], v[178:181], v[194:197], v[66:69]
	v_mfma_f32_16x16x32_bf16 v[114:117], v[170:173], v[202:205], v[114:117]
	v_mfma_f32_16x16x32_bf16 v[110:113], v[178:181], v[202:205], v[110:113]
	v_mfma_f32_16x16x32_bf16 v[98:101], v[170:173], v[210:213], v[98:101]
	v_mfma_f32_16x16x32_bf16 v[94:97], v[178:181], v[210:213], v[94:97]
	v_mfma_f32_16x16x32_bf16 v[126:129], v[150:153], v[182:185], v[138:141]
	v_mfma_f32_16x16x32_bf16 v[138:141], v[154:157], v[186:189], v[126:129]
	v_mfma_f32_16x16x32_bf16 v[126:129], v[158:161], v[182:185], v[134:137]
	v_mfma_f32_16x16x32_bf16 v[122:125], v[150:153], v[190:193], v[122:125]
	v_mfma_f32_16x16x32_bf16 v[118:121], v[158:161], v[190:193], v[118:121]
	v_mfma_f32_16x16x32_bf16 v[106:109], v[150:153], v[198:201], v[106:109]
	v_mfma_f32_16x16x32_bf16 v[102:105], v[158:161], v[198:201], v[102:105]
	v_mfma_f32_16x16x32_bf16 v[90:93], v[150:153], v[206:209], v[90:93]
	v_mfma_f32_16x16x32_bf16 v[86:89], v[158:161], v[206:209], v[86:89]
	v_mfma_f32_16x16x32_bf16 v[134:137], v[162:165], v[186:189], v[126:129]
	v_mfma_f32_16x16x32_bf16 v[122:125], v[154:157], v[194:197], v[122:125]
	v_mfma_f32_16x16x32_bf16 v[118:121], v[162:165], v[194:197], v[118:121]
	v_mfma_f32_16x16x32_bf16 v[106:109], v[154:157], v[202:205], v[106:109]
	v_mfma_f32_16x16x32_bf16 v[102:105], v[162:165], v[202:205], v[102:105]
	v_mfma_f32_16x16x32_bf16 v[90:93], v[154:157], v[210:213], v[90:93]
	v_mfma_f32_16x16x32_bf16 v[86:89], v[162:165], v[210:213], v[86:89]
	s_barrier
	ds_read_b128 v[190:193], v245 offset:16384
	ds_read_b128 v[194:197], v245 offset:17408
	ds_read_b128 v[182:185], v245 offset:18432
	ds_read_b128 v[186:189], v245 offset:19456
	ds_read_b128 v[142:145], v245 offset:20480
	ds_read_b128 v[146:149], v245 offset:21504
	ds_read_b128 v[126:129], v245 offset:22528
	ds_read_b128 v[130:133], v245 offset:23552
	s_or_b64 s[90:91], s[80:81], s[90:91]
	s_xor_b64 s[92:93], s[90:91], -1
	s_mov_b64 s[94:95], -1
	s_and_b64 vcc, exec, s[92:93]
	s_cbranch_vccz .LBB0_248
	s_waitcnt vmcnt(2)
	s_mov_b64 s[94:95], 0

.LBB0_250:
	s_waitcnt lgkmcnt(0)
	s_barrier
	s_waitcnt lgkmcnt(0)
	v_mfma_f32_16x16x32_bf16 v[82:85], v[166:169], v[190:193], v[82:85]
	v_mfma_f32_16x16x32_bf16 v[78:81], v[174:177], v[190:193], v[78:81]
	v_mfma_f32_16x16x32_bf16 v[50:53], v[166:169], v[182:185], v[50:53]
	v_mfma_f32_16x16x32_bf16 v[46:49], v[174:177], v[182:185], v[46:49]
	v_mfma_f32_16x16x32_bf16 v[34:37], v[166:169], v[142:145], v[34:37]
	v_mfma_f32_16x16x32_bf16 v[30:33], v[174:177], v[142:145], v[30:33]
	v_mfma_f32_16x16x32_bf16 v[18:21], v[166:169], v[126:129], v[18:21]
	v_mfma_f32_16x16x32_bf16 v[10:13], v[174:177], v[126:129], v[10:13]
	v_mfma_f32_16x16x32_bf16 v[82:85], v[170:173], v[194:197], v[82:85]
	v_mfma_f32_16x16x32_bf16 v[78:81], v[178:181], v[194:197], v[78:81]
	v_mfma_f32_16x16x32_bf16 v[50:53], v[170:173], v[186:189], v[50:53]
	v_mfma_f32_16x16x32_bf16 v[46:49], v[178:181], v[186:189], v[46:49]
	v_mfma_f32_16x16x32_bf16 v[34:37], v[170:173], v[146:149], v[34:37]
	v_mfma_f32_16x16x32_bf16 v[30:33], v[178:181], v[146:149], v[30:33]
	v_mfma_f32_16x16x32_bf16 v[18:21], v[170:173], v[130:133], v[18:21]
	v_mfma_f32_16x16x32_bf16 v[10:13], v[178:181], v[130:133], v[10:13]
	v_mfma_f32_16x16x32_bf16 v[74:77], v[150:153], v[190:193], v[74:77]
	v_mfma_f32_16x16x32_bf16 v[70:73], v[158:161], v[190:193], v[70:73]
	v_mfma_f32_16x16x32_bf16 v[42:45], v[150:153], v[182:185], v[42:45]
	v_mfma_f32_16x16x32_bf16 v[38:41], v[158:161], v[182:185], v[38:41]
	v_mfma_f32_16x16x32_bf16 v[26:29], v[150:153], v[142:145], v[26:29]
	v_mfma_f32_16x16x32_bf16 v[22:25], v[158:161], v[142:145], v[22:25]
	v_mfma_f32_16x16x32_bf16 v[6:9], v[150:153], v[126:129], v[6:9]
	v_mfma_f32_16x16x32_bf16 v[2:5], v[158:161], v[126:129], v[2:5]
	v_mfma_f32_16x16x32_bf16 v[74:77], v[154:157], v[194:197], v[74:77]
	v_mfma_f32_16x16x32_bf16 v[70:73], v[162:165], v[194:197], v[70:73]
	v_mfma_f32_16x16x32_bf16 v[42:45], v[154:157], v[186:189], v[42:45]
	v_mfma_f32_16x16x32_bf16 v[38:41], v[162:165], v[186:189], v[38:41]
	v_mfma_f32_16x16x32_bf16 v[26:29], v[154:157], v[146:149], v[26:29]
	v_mfma_f32_16x16x32_bf16 v[22:25], v[162:165], v[146:149], v[22:25]
	v_mfma_f32_16x16x32_bf16 v[6:9], v[154:157], v[130:133], v[6:9]
	v_mfma_f32_16x16x32_bf16 v[2:5], v[162:165], v[130:133], v[2:5]
	s_barrier
	v_add_u32_e32 v0, 0x18000, v235
	ds_read_b128 v[166:169], v0
	ds_read_b128 v[170:173], v0 offset:1024
	ds_read_b128 v[174:177], v0 offset:2048
	ds_read_b128 v[178:181], v0 offset:3072
	v_add_u32_e32 v0, 0x1c000, v235
	ds_read_b128 v[150:153], v0
	ds_read_b128 v[154:157], v0 offset:1024
	ds_read_b128 v[158:161], v0 offset:2048
	ds_read_b128 v[162:165], v0 offset:3072
	ds_read_b128 v[206:209], v245 offset:32768
	ds_read_b128 v[210:213], v245 offset:33792
	ds_read_b128 v[198:201], v245 offset:34816
	ds_read_b128 v[202:205], v245 offset:35840
	ds_read_b128 v[190:193], v245 offset:36864
	ds_read_b128 v[194:197], v245 offset:37888
	ds_read_b128 v[182:185], v245 offset:38912
	ds_read_b128 v[186:189], v245 offset:39936
	s_mov_b64 s[94:95], -1
	s_and_b64 vcc, exec, s[92:93]
	s_cbranch_vccz .LBB0_252
	s_waitcnt vmcnt(0)
	s_mov_b64 s[94:95], 0

.LBB0_254:
	s_waitcnt lgkmcnt(0)
	s_barrier
	s_waitcnt lgkmcnt(0)
	v_mfma_f32_16x16x32_bf16 v[54:57], v[166:169], v[206:209], v[54:57]
	v_mfma_f32_16x16x32_bf16 v[146:149], v[170:173], v[210:213], v[54:57]
	v_mfma_f32_16x16x32_bf16 v[54:57], v[174:177], v[206:209], v[58:61]
	v_mfma_f32_16x16x32_bf16 v[142:145], v[178:181], v[210:213], v[54:57]
	v_mfma_f32_16x16x32_bf16 v[54:57], v[166:169], v[198:201], v[62:65]
	v_mfma_f32_16x16x32_bf16 v[130:133], v[170:173], v[202:205], v[54:57]
	v_mfma_f32_16x16x32_bf16 v[54:57], v[174:177], v[198:201], v[66:69]
	v_mfma_f32_16x16x32_bf16 v[126:129], v[178:181], v[202:205], v[54:57]
	v_mfma_f32_16x16x32_bf16 v[54:57], v[166:169], v[190:193], v[114:117]
	v_mfma_f32_16x16x32_bf16 v[114:117], v[170:173], v[194:197], v[54:57]
	v_mfma_f32_16x16x32_bf16 v[54:57], v[174:177], v[190:193], v[110:113]
	v_mfma_f32_16x16x32_bf16 v[110:113], v[178:181], v[194:197], v[54:57]
	v_mfma_f32_16x16x32_bf16 v[54:57], v[166:169], v[182:185], v[98:101]
	v_mfma_f32_16x16x32_bf16 v[98:101], v[170:173], v[186:189], v[54:57]
	v_mfma_f32_16x16x32_bf16 v[54:57], v[174:177], v[182:185], v[94:97]
	v_mfma_f32_16x16x32_bf16 v[94:97], v[178:181], v[186:189], v[54:57]
	v_mfma_f32_16x16x32_bf16 v[54:57], v[150:153], v[206:209], v[138:141]
	v_mfma_f32_16x16x32_bf16 v[138:141], v[154:157], v[210:213], v[54:57]
	v_mfma_f32_16x16x32_bf16 v[54:57], v[158:161], v[206:209], v[134:137]
	v_mfma_f32_16x16x32_bf16 v[134:137], v[162:165], v[210:213], v[54:57]
	v_mfma_f32_16x16x32_bf16 v[54:57], v[150:153], v[198:201], v[122:125]
	v_mfma_f32_16x16x32_bf16 v[122:125], v[154:157], v[202:205], v[54:57]
	v_mfma_f32_16x16x32_bf16 v[54:57], v[158:161], v[198:201], v[118:121]
	v_mfma_f32_16x16x32_bf16 v[118:121], v[162:165], v[202:205], v[54:57]
	v_mfma_f32_16x16x32_bf16 v[54:57], v[150:153], v[190:193], v[106:109]
	v_mfma_f32_16x16x32_bf16 v[106:109], v[154:157], v[194:197], v[54:57]
	v_mfma_f32_16x16x32_bf16 v[54:57], v[158:161], v[190:193], v[102:105]
	v_mfma_f32_16x16x32_bf16 v[102:105], v[162:165], v[194:197], v[54:57]
	v_mfma_f32_16x16x32_bf16 v[54:57], v[150:153], v[182:185], v[90:93]
	v_mfma_f32_16x16x32_bf16 v[90:93], v[154:157], v[186:189], v[54:57]
	v_mfma_f32_16x16x32_bf16 v[54:57], v[158:161], v[182:185], v[86:89]
	v_mfma_f32_16x16x32_bf16 v[86:89], v[162:165], v[186:189], v[54:57]
	s_barrier
	ds_read_b128 v[190:193], v245 offset:49152
	ds_read_b128 v[194:197], v245 offset:50176
	ds_read_b128 v[182:185], v245 offset:51200
	ds_read_b128 v[186:189], v245 offset:52224
	ds_read_b128 v[62:65], v245 offset:53248
	ds_read_b128 v[66:69], v245 offset:54272
	ds_read_b128 v[54:57], v245 offset:55296
	ds_read_b128 v[58:61], v245 offset:56320
	s_andn2_b64 vcc, exec, s[90:91]
	s_cbranch_vccnz .LBB0_245
	s_mov_b32 m0, s1
	v_lshl_add_u64 v[198:199], v[232:233], 0, s[16:17]
	s_add_u32 s86, s86, 0x80080
	global_load_lds_dwordx4 v[198:199], off
	v_lshl_add_u64 v[198:199], v[230:231], 0, s[16:17]
	s_mov_b32 m0, s38
	s_addc_u32 s87, s87, 0
	global_load_lds_dwordx4 v[198:199], off
	v_lshl_add_u64 v[198:199], s[86:87], 0, v[216:217]
	s_mov_b32 m0, s46
	s_nop 0
	global_load_lds_dwordx4 v[198:199], off
	v_lshl_add_u64 v[198:199], s[86:87], 0, v[220:221]
	s_mov_b32 m0, s47
	s_nop 0
	global_load_lds_dwordx4 v[198:199], off
	v_lshl_add_u64 v[198:199], v[228:229], 0, s[16:17]
	s_mov_b32 m0, s40
	s_nop 0
	global_load_lds_dwordx4 v[198:199], off
	v_lshl_add_u64 v[198:199], v[226:227], 0, s[16:17]
	s_mov_b32 m0, s41
	s_nop 0
	global_load_lds_dwordx4 v[198:199], off
	s_waitcnt vmcnt(8)
	s_branch .LBB0_245

.LBB0_1310:
	s_waitcnt lgkmcnt(0)
	s_barrier
	s_waitcnt lgkmcnt(0)
	v_mfma_f32_16x16x32_bf16 v[78:81], v[150:153], v[190:193], v[78:81]
	v_mfma_f32_16x16x32_bf16 v[86:89], v[158:161], v[190:193], v[86:89]
	v_mfma_f32_16x16x32_bf16 v[110:113], v[150:153], v[182:185], v[110:113]
	v_mfma_f32_16x16x32_bf16 v[114:117], v[158:161], v[182:185], v[114:117]
	v_mfma_f32_16x16x32_bf16 v[130:133], v[150:153], v[174:177], v[130:133]
	v_mfma_f32_16x16x32_bf16 v[118:121], v[158:161], v[174:177], v[118:121]
	v_mfma_f32_16x16x32_bf16 v[90:93], v[150:153], v[166:169], v[90:93]
	v_mfma_f32_16x16x32_bf16 v[82:85], v[158:161], v[166:169], v[82:85]
	v_mfma_f32_16x16x32_bf16 v[78:81], v[154:157], v[194:197], v[78:81]
	v_mfma_f32_16x16x32_bf16 v[86:89], v[162:165], v[194:197], v[86:89]
	v_mfma_f32_16x16x32_bf16 v[110:113], v[154:157], v[186:189], v[110:113]
	v_mfma_f32_16x16x32_bf16 v[114:117], v[162:165], v[186:189], v[114:117]
	v_mfma_f32_16x16x32_bf16 v[130:133], v[154:157], v[178:181], v[130:133]
	v_mfma_f32_16x16x32_bf16 v[118:121], v[162:165], v[178:181], v[118:121]
	v_mfma_f32_16x16x32_bf16 v[90:93], v[154:157], v[170:173], v[90:93]
	v_mfma_f32_16x16x32_bf16 v[82:85], v[162:165], v[170:173], v[82:85]
	v_mfma_f32_16x16x32_bf16 v[94:97], v[134:137], v[190:193], v[94:97]
	v_mfma_f32_16x16x32_bf16 v[98:101], v[142:145], v[190:193], v[98:101]
	v_mfma_f32_16x16x32_bf16 v[122:125], v[134:137], v[182:185], v[122:125]
	v_mfma_f32_16x16x32_bf16 v[126:129], v[142:145], v[182:185], v[126:129]
	v_mfma_f32_16x16x32_bf16 v[106:109], v[134:137], v[174:177], v[106:109]
	v_mfma_f32_16x16x32_bf16 v[102:105], v[142:145], v[174:177], v[102:105]
	v_mfma_f32_16x16x32_bf16 v[66:69], v[134:137], v[166:169], v[66:69]
	v_mfma_f32_16x16x32_bf16 v[62:65], v[142:145], v[166:169], v[62:65]
	v_mfma_f32_16x16x32_bf16 v[94:97], v[138:141], v[194:197], v[94:97]
	v_mfma_f32_16x16x32_bf16 v[98:101], v[146:149], v[194:197], v[98:101]
	v_mfma_f32_16x16x32_bf16 v[122:125], v[138:141], v[186:189], v[122:125]
	v_mfma_f32_16x16x32_bf16 v[126:129], v[146:149], v[186:189], v[126:129]
	v_mfma_f32_16x16x32_bf16 v[106:109], v[138:141], v[178:181], v[106:109]
	v_mfma_f32_16x16x32_bf16 v[102:105], v[146:149], v[178:181], v[102:105]
	v_mfma_f32_16x16x32_bf16 v[66:69], v[138:141], v[170:173], v[66:69]
	v_mfma_f32_16x16x32_bf16 v[62:65], v[146:149], v[170:173], v[62:65]
	s_barrier
	s_cmp_ge_u32 s60, s41
	s_cbranch_scc1 .LBB0_1321
.LBB0_1311:
	s_cmp_eq_u32 s60, s74
	s_cselect_b64 s[10:11], -1, 0
	s_or_b32 s14, s60, 1
	s_add_i32 s60, s60, 2
	s_mov_b32 s61, s15
	s_lshl_b64 s[62:63], s[60:61], 7
	v_add_u32_e32 v0, 0x10000, v235
	s_add_u32 s61, s56, s62
	ds_read_b128 v[150:153], v0
	ds_read_b128 v[154:157], v0 offset:1024
	ds_read_b128 v[158:161], v0 offset:2048
	ds_read_b128 v[162:165], v0 offset:3072
	v_add_u32_e32 v0, 0x14000, v235
	s_addc_u32 s66, s57, s63
	ds_read_b128 v[134:137], v0
	ds_read_b128 v[138:141], v0 offset:1024
	ds_read_b128 v[142:145], v0 offset:2048
	ds_read_b128 v[146:149], v0 offset:3072
	s_and_b64 s[64:65], s[10:11], exec
	s_cselect_b32 s62, 0, s62
	s_cselect_b32 s63, 0, s63
	s_add_u32 s62, s42, s62
	s_addc_u32 s63, s43, s63
	s_and_b64 s[64:65], s[10:11], exec
	s_cselect_b32 s65, s53, s66
	s_cselect_b32 s64, s52, s61
	s_lshl_b64 s[66:67], s[14:15], 7
	s_add_u32 s66, s33, s66
	s_addc_u32 s67, s84, s67
	v_lshl_add_u64 v[224:225], s[66:67], 0, v[202:203]
	s_add_i32 m0, s21, 0xc000
	ds_read_b128 v[166:169], v236
	ds_read_b128 v[170:173], v236 offset:1024
	ds_read_b128 v[174:177], v236 offset:2048
	ds_read_b128 v[178:181], v236 offset:3072
	ds_read_b128 v[182:185], v236 offset:4096
	ds_read_b128 v[186:189], v236 offset:5120
	ds_read_b128 v[190:193], v236 offset:6144
	ds_read_b128 v[194:197], v236 offset:7168
	global_load_lds_dwordx4 v[224:225], off
	v_lshl_add_u64 v[224:225], s[66:67], 0, v[198:199]
	s_add_i32 m0, s21, 0xe000
	s_nop 0
	global_load_lds_dwordx4 v[224:225], off
	s_waitcnt vmcnt(8)
	s_waitcnt lgkmcnt(0)
	s_barrier
	s_waitcnt lgkmcnt(0)
	v_mfma_f32_16x16x32_bf16 v[30:33], v[150:153], v[166:169], v[30:33]
	v_mfma_f32_16x16x32_bf16 v[34:37], v[158:161], v[166:169], v[34:37]
	v_mfma_f32_16x16x32_bf16 v[6:9], v[150:153], v[174:177], v[6:9]
	v_mfma_f32_16x16x32_bf16 v[2:5], v[158:161], v[174:177], v[2:5]
	v_mfma_f32_16x16x32_bf16 v[22:25], v[150:153], v[182:185], v[22:25]
	v_mfma_f32_16x16x32_bf16 v[26:29], v[158:161], v[182:185], v[26:29]
	v_mfma_f32_16x16x32_bf16 v[54:57], v[150:153], v[190:193], v[54:57]
	v_mfma_f32_16x16x32_bf16 v[58:61], v[158:161], v[190:193], v[58:61]
	v_mfma_f32_16x16x32_bf16 v[30:33], v[154:157], v[170:173], v[30:33]
	v_mfma_f32_16x16x32_bf16 v[34:37], v[162:165], v[170:173], v[34:37]
	v_mfma_f32_16x16x32_bf16 v[6:9], v[154:157], v[178:181], v[6:9]
	v_mfma_f32_16x16x32_bf16 v[2:5], v[162:165], v[178:181], v[2:5]
	v_mfma_f32_16x16x32_bf16 v[22:25], v[154:157], v[186:189], v[22:25]
	v_mfma_f32_16x16x32_bf16 v[26:29], v[162:165], v[186:189], v[26:29]
	v_mfma_f32_16x16x32_bf16 v[54:57], v[154:157], v[194:197], v[54:57]
	v_mfma_f32_16x16x32_bf16 v[58:61], v[162:165], v[194:197], v[58:61]
	v_mfma_f32_16x16x32_bf16 v[46:49], v[134:137], v[166:169], v[46:49]
	v_mfma_f32_16x16x32_bf16 v[50:53], v[142:145], v[166:169], v[50:53]
	v_mfma_f32_16x16x32_bf16 v[10:13], v[134:137], v[174:177], v[10:13]
	v_mfma_f32_16x16x32_bf16 v[18:21], v[142:145], v[174:177], v[18:21]
	v_mfma_f32_16x16x32_bf16 v[38:41], v[134:137], v[182:185], v[38:41]
	v_mfma_f32_16x16x32_bf16 v[42:45], v[142:145], v[182:185], v[42:45]
	v_mfma_f32_16x16x32_bf16 v[70:73], v[134:137], v[190:193], v[70:73]
	v_mfma_f32_16x16x32_bf16 v[74:77], v[142:145], v[190:193], v[74:77]
	v_mfma_f32_16x16x32_bf16 v[46:49], v[138:141], v[170:173], v[46:49]
	v_mfma_f32_16x16x32_bf16 v[50:53], v[146:149], v[170:173], v[50:53]
	v_mfma_f32_16x16x32_bf16 v[10:13], v[138:141], v[178:181], v[10:13]
	v_mfma_f32_16x16x32_bf16 v[18:21], v[146:149], v[178:181], v[18:21]
	v_mfma_f32_16x16x32_bf16 v[38:41], v[138:141], v[186:189], v[38:41]
	v_mfma_f32_16x16x32_bf16 v[42:45], v[146:149], v[186:189], v[42:45]
	v_mfma_f32_16x16x32_bf16 v[70:73], v[138:141], v[194:197], v[70:73]
	v_mfma_f32_16x16x32_bf16 v[74:77], v[146:149], v[194:197], v[74:77]
	s_barrier
	ds_read_b128 v[190:193], v236 offset:16384
	ds_read_b128 v[194:197], v236 offset:17408
	ds_read_b128 v[182:185], v236 offset:18432
	ds_read_b128 v[186:189], v236 offset:19456
	ds_read_b128 v[174:177], v236 offset:20480
	ds_read_b128 v[178:181], v236 offset:21504
	ds_read_b128 v[166:169], v236 offset:22528
	ds_read_b128 v[170:173], v236 offset:23552
	s_and_b64 s[10:11], s[58:59], s[10:11]
	s_mov_b64 s[66:67], -1
	s_and_b64 vcc, exec, s[10:11]
	v_lshl_add_u64 v[230:231], s[62:63], 0, v[200:201]
	v_lshl_add_u64 v[228:229], s[62:63], 0, v[14:15]
	v_lshl_add_u64 v[226:227], s[64:65], 0, v[202:203]
	v_lshl_add_u64 v[224:225], s[64:65], 0, v[198:199]
	s_cbranch_vccnz .LBB0_1313
	s_mov_b32 m0, s22
	s_add_u32 s66, s62, s0
	global_load_lds_dwordx4 v[230:231], off
	s_mov_b32 m0, s23
	s_addc_u32 s67, s63, 0
	global_load_lds_dwordx4 v[228:229], off
	v_lshl_add_u64 v[240:241], s[66:67], 0, v[200:201]
	s_mov_b32 m0, s25
	s_nop 0
	global_load_lds_dwordx4 v[240:241], off
	v_lshl_add_u64 v[240:241], s[66:67], 0, v[14:15]
	s_mov_b32 m0, s28
	s_mov_b64 s[66:67], 0
	global_load_lds_dwordx4 v[240:241], off
	s_mov_b32 m0, s21
	s_nop 0
	global_load_lds_dwordx4 v[226:227], off
	s_mov_b32 m0, s29
	s_nop 0
	global_load_lds_dwordx4 v[224:225], off
	s_waitcnt vmcnt(8)

.LBB0_1315:
	s_waitcnt lgkmcnt(0)
	s_xor_b64 s[66:67], s[10:11], -1
	s_barrier
	s_waitcnt lgkmcnt(0)
	v_mfma_f32_16x16x32_bf16 v[78:81], v[150:153], v[190:193], v[78:81]
	v_mfma_f32_16x16x32_bf16 v[86:89], v[158:161], v[190:193], v[86:89]
	v_mfma_f32_16x16x32_bf16 v[110:113], v[150:153], v[182:185], v[110:113]
	v_mfma_f32_16x16x32_bf16 v[114:117], v[158:161], v[182:185], v[114:117]
	v_mfma_f32_16x16x32_bf16 v[130:133], v[150:153], v[174:177], v[130:133]
	v_mfma_f32_16x16x32_bf16 v[118:121], v[158:161], v[174:177], v[118:121]
	v_mfma_f32_16x16x32_bf16 v[90:93], v[150:153], v[166:169], v[90:93]
	v_mfma_f32_16x16x32_bf16 v[82:85], v[158:161], v[166:169], v[82:85]
	v_mfma_f32_16x16x32_bf16 v[78:81], v[154:157], v[194:197], v[78:81]
	v_mfma_f32_16x16x32_bf16 v[86:89], v[162:165], v[194:197], v[86:89]
	v_mfma_f32_16x16x32_bf16 v[110:113], v[154:157], v[186:189], v[110:113]
	v_mfma_f32_16x16x32_bf16 v[114:117], v[162:165], v[186:189], v[114:117]
	v_mfma_f32_16x16x32_bf16 v[130:133], v[154:157], v[178:181], v[130:133]
	v_mfma_f32_16x16x32_bf16 v[118:121], v[162:165], v[178:181], v[118:121]
	v_mfma_f32_16x16x32_bf16 v[90:93], v[154:157], v[170:173], v[90:93]
	v_mfma_f32_16x16x32_bf16 v[82:85], v[162:165], v[170:173], v[82:85]
	v_mfma_f32_16x16x32_bf16 v[94:97], v[134:137], v[190:193], v[94:97]
	v_mfma_f32_16x16x32_bf16 v[98:101], v[142:145], v[190:193], v[98:101]
	v_mfma_f32_16x16x32_bf16 v[122:125], v[134:137], v[182:185], v[122:125]
	v_mfma_f32_16x16x32_bf16 v[126:129], v[142:145], v[182:185], v[126:129]
	v_mfma_f32_16x16x32_bf16 v[106:109], v[134:137], v[174:177], v[106:109]
	v_mfma_f32_16x16x32_bf16 v[102:105], v[142:145], v[174:177], v[102:105]
	v_mfma_f32_16x16x32_bf16 v[66:69], v[134:137], v[166:169], v[66:69]
	v_mfma_f32_16x16x32_bf16 v[62:65], v[142:145], v[166:169], v[62:65]
	v_mfma_f32_16x16x32_bf16 v[94:97], v[138:141], v[194:197], v[94:97]
	v_mfma_f32_16x16x32_bf16 v[98:101], v[146:149], v[194:197], v[98:101]
	v_mfma_f32_16x16x32_bf16 v[122:125], v[138:141], v[186:189], v[122:125]
	v_mfma_f32_16x16x32_bf16 v[126:129], v[146:149], v[186:189], v[126:129]
	v_mfma_f32_16x16x32_bf16 v[106:109], v[138:141], v[178:181], v[106:109]
	v_mfma_f32_16x16x32_bf16 v[102:105], v[146:149], v[178:181], v[102:105]
	v_mfma_f32_16x16x32_bf16 v[66:69], v[138:141], v[170:173], v[66:69]
	v_mfma_f32_16x16x32_bf16 v[62:65], v[146:149], v[170:173], v[62:65]
	s_barrier
	v_add_u32_e32 v0, 0x18000, v235
	ds_read_b128 v[150:153], v0
	ds_read_b128 v[154:157], v0 offset:1024
	ds_read_b128 v[158:161], v0 offset:2048
	ds_read_b128 v[162:165], v0 offset:3072
	v_add_u32_e32 v0, 0x1c000, v235
	ds_read_b128 v[134:137], v0
	ds_read_b128 v[138:141], v0 offset:1024
	ds_read_b128 v[142:145], v0 offset:2048
	ds_read_b128 v[146:149], v0 offset:3072
	ds_read_b128 v[190:193], v236 offset:32768
	ds_read_b128 v[194:197], v236 offset:33792
	ds_read_b128 v[182:185], v236 offset:34816
	ds_read_b128 v[186:189], v236 offset:35840
	ds_read_b128 v[174:177], v236 offset:36864
	ds_read_b128 v[178:181], v236 offset:37888
	ds_read_b128 v[166:169], v236 offset:38912
	ds_read_b128 v[170:173], v236 offset:39936
	v_cndmask_b32_e64 v0, 0, 1, s[66:67]
	v_cmp_ne_u32_e64 s[10:11], 1, v0
	s_andn2_b64 vcc, exec, s[66:67]
	s_mov_b64 s[66:67], -1
	s_cbranch_vccnz .LBB0_1317
	s_add_u32 s64, s64, s0
	s_addc_u32 s65, s65, 0
	s_mov_b32 m0, s36
	v_lshl_add_u64 v[240:241], s[64:65], 0, v[202:203]
	global_load_lds_dwordx4 v[240:241], off
	v_lshl_add_u64 v[240:241], s[64:65], 0, v[198:199]
	s_mov_b32 m0, s38
	s_mov_b64 s[66:67], 0
	global_load_lds_dwordx4 v[240:241], off
	s_waitcnt vmcnt(8)

.LBB0_1319:
	s_waitcnt lgkmcnt(0)
	s_barrier
	s_waitcnt lgkmcnt(0)
	v_mfma_f32_16x16x32_bf16 v[30:33], v[150:153], v[190:193], v[30:33]
	v_mfma_f32_16x16x32_bf16 v[34:37], v[158:161], v[190:193], v[34:37]
	v_mfma_f32_16x16x32_bf16 v[6:9], v[150:153], v[182:185], v[6:9]
	v_mfma_f32_16x16x32_bf16 v[2:5], v[158:161], v[182:185], v[2:5]
	v_mfma_f32_16x16x32_bf16 v[22:25], v[150:153], v[174:177], v[22:25]
	v_mfma_f32_16x16x32_bf16 v[26:29], v[158:161], v[174:177], v[26:29]
	v_mfma_f32_16x16x32_bf16 v[54:57], v[150:153], v[166:169], v[54:57]
	v_mfma_f32_16x16x32_bf16 v[58:61], v[158:161], v[166:169], v[58:61]
	v_mfma_f32_16x16x32_bf16 v[30:33], v[154:157], v[194:197], v[30:33]
	v_mfma_f32_16x16x32_bf16 v[34:37], v[162:165], v[194:197], v[34:37]
	v_mfma_f32_16x16x32_bf16 v[6:9], v[154:157], v[186:189], v[6:9]
	v_mfma_f32_16x16x32_bf16 v[2:5], v[162:165], v[186:189], v[2:5]
	v_mfma_f32_16x16x32_bf16 v[22:25], v[154:157], v[178:181], v[22:25]
	v_mfma_f32_16x16x32_bf16 v[26:29], v[162:165], v[178:181], v[26:29]
	v_mfma_f32_16x16x32_bf16 v[54:57], v[154:157], v[170:173], v[54:57]
	v_mfma_f32_16x16x32_bf16 v[58:61], v[162:165], v[170:173], v[58:61]
	v_mfma_f32_16x16x32_bf16 v[46:49], v[134:137], v[190:193], v[46:49]
	v_mfma_f32_16x16x32_bf16 v[50:53], v[142:145], v[190:193], v[50:53]
	v_mfma_f32_16x16x32_bf16 v[10:13], v[134:137], v[182:185], v[10:13]
	v_mfma_f32_16x16x32_bf16 v[18:21], v[142:145], v[182:185], v[18:21]
	v_mfma_f32_16x16x32_bf16 v[38:41], v[134:137], v[174:177], v[38:41]
	v_mfma_f32_16x16x32_bf16 v[42:45], v[142:145], v[174:177], v[42:45]
	v_mfma_f32_16x16x32_bf16 v[70:73], v[134:137], v[166:169], v[70:73]
	v_mfma_f32_16x16x32_bf16 v[74:77], v[142:145], v[166:169], v[74:77]
	v_mfma_f32_16x16x32_bf16 v[46:49], v[138:141], v[194:197], v[46:49]
	v_mfma_f32_16x16x32_bf16 v[50:53], v[146:149], v[194:197], v[50:53]
	v_mfma_f32_16x16x32_bf16 v[10:13], v[138:141], v[186:189], v[10:13]
	v_mfma_f32_16x16x32_bf16 v[18:21], v[146:149], v[186:189], v[18:21]
	v_mfma_f32_16x16x32_bf16 v[38:41], v[138:141], v[178:181], v[38:41]
	v_mfma_f32_16x16x32_bf16 v[42:45], v[146:149], v[178:181], v[42:45]
	v_mfma_f32_16x16x32_bf16 v[70:73], v[138:141], v[170:173], v[70:73]
	v_mfma_f32_16x16x32_bf16 v[74:77], v[146:149], v[170:173], v[74:77]
	s_barrier
	ds_read_b128 v[190:193], v236 offset:49152
	ds_read_b128 v[194:197], v236 offset:50176
	ds_read_b128 v[182:185], v236 offset:51200
	ds_read_b128 v[186:189], v236 offset:52224
	ds_read_b128 v[174:177], v236 offset:53248
	ds_read_b128 v[178:181], v236 offset:54272
	ds_read_b128 v[166:169], v236 offset:55296
	ds_read_b128 v[170:173], v236 offset:56320
	s_and_b64 vcc, exec, s[10:11]
	s_cbranch_vccnz .LBB0_1310
	s_mov_b32 m0, s68
	v_lshl_add_u64 v[230:231], v[230:231], 0, s[16:17]
	s_add_u32 s10, s62, s0
	global_load_lds_dwordx4 v[230:231], off
	v_lshl_add_u64 v[228:229], v[228:229], 0, s[16:17]
	s_mov_b32 m0, s69
	s_addc_u32 s11, s63, 0
	global_load_lds_dwordx4 v[228:229], off
	v_lshl_add_u64 v[228:229], s[10:11], 0, v[200:201]
	v_lshl_add_u64 v[228:229], v[228:229], 0, s[16:17]
	s_mov_b32 m0, s72
	v_lshl_add_u64 v[226:227], v[226:227], 0, s[16:17]
	global_load_lds_dwordx4 v[228:229], off
	v_lshl_add_u64 v[228:229], s[10:11], 0, v[14:15]
	v_lshl_add_u64 v[228:229], v[228:229], 0, s[16:17]
	s_mov_b32 m0, s73
	v_lshl_add_u64 v[224:225], v[224:225], 0, s[16:17]
	global_load_lds_dwordx4 v[228:229], off
	s_mov_b32 m0, s70
	s_nop 0
	global_load_lds_dwordx4 v[226:227], off
	s_mov_b32 m0, s71
	s_nop 0
	global_load_lds_dwordx4 v[224:225], off
	s_waitcnt vmcnt(8)
	s_branch .LBB0_1310

.LBB0_1532:
	s_waitcnt lgkmcnt(0)
	s_barrier
	s_waitcnt lgkmcnt(0)
	v_mfma_f32_16x16x32_bf16 v[66:69], v[150:153], v[190:193], v[66:69]
	v_mfma_f32_16x16x32_bf16 v[62:65], v[158:161], v[190:193], v[62:65]
	v_mfma_f32_16x16x32_bf16 v[50:53], v[150:153], v[182:185], v[50:53]
	v_mfma_f32_16x16x32_bf16 v[46:49], v[158:161], v[182:185], v[46:49]
	v_mfma_f32_16x16x32_bf16 v[34:37], v[150:153], v[174:177], v[34:37]
	v_mfma_f32_16x16x32_bf16 v[30:33], v[158:161], v[174:177], v[30:33]
	v_mfma_f32_16x16x32_bf16 v[18:21], v[150:153], v[166:169], v[18:21]
	v_mfma_f32_16x16x32_bf16 v[10:13], v[158:161], v[166:169], v[10:13]
	v_mfma_f32_16x16x32_bf16 v[66:69], v[154:157], v[194:197], v[66:69]
	v_mfma_f32_16x16x32_bf16 v[62:65], v[162:165], v[194:197], v[62:65]
	v_mfma_f32_16x16x32_bf16 v[50:53], v[154:157], v[186:189], v[50:53]
	v_mfma_f32_16x16x32_bf16 v[46:49], v[162:165], v[186:189], v[46:49]
	v_mfma_f32_16x16x32_bf16 v[34:37], v[154:157], v[178:181], v[34:37]
	v_mfma_f32_16x16x32_bf16 v[30:33], v[162:165], v[178:181], v[30:33]
	v_mfma_f32_16x16x32_bf16 v[18:21], v[154:157], v[170:173], v[18:21]
	v_mfma_f32_16x16x32_bf16 v[10:13], v[162:165], v[170:173], v[10:13]
	v_mfma_f32_16x16x32_bf16 v[58:61], v[134:137], v[190:193], v[58:61]
	v_mfma_f32_16x16x32_bf16 v[54:57], v[142:145], v[190:193], v[54:57]
	v_mfma_f32_16x16x32_bf16 v[42:45], v[134:137], v[182:185], v[42:45]
	v_mfma_f32_16x16x32_bf16 v[38:41], v[142:145], v[182:185], v[38:41]
	v_mfma_f32_16x16x32_bf16 v[26:29], v[134:137], v[174:177], v[26:29]
	v_mfma_f32_16x16x32_bf16 v[22:25], v[142:145], v[174:177], v[22:25]
	v_mfma_f32_16x16x32_bf16 v[6:9], v[134:137], v[166:169], v[6:9]
	v_mfma_f32_16x16x32_bf16 v[2:5], v[142:145], v[166:169], v[2:5]
	v_mfma_f32_16x16x32_bf16 v[58:61], v[138:141], v[194:197], v[58:61]
	v_mfma_f32_16x16x32_bf16 v[54:57], v[146:149], v[194:197], v[54:57]
	v_mfma_f32_16x16x32_bf16 v[42:45], v[138:141], v[186:189], v[42:45]
	v_mfma_f32_16x16x32_bf16 v[38:41], v[146:149], v[186:189], v[38:41]
	v_mfma_f32_16x16x32_bf16 v[26:29], v[138:141], v[178:181], v[26:29]
	v_mfma_f32_16x16x32_bf16 v[22:25], v[146:149], v[178:181], v[22:25]
	v_mfma_f32_16x16x32_bf16 v[6:9], v[138:141], v[170:173], v[6:9]
	v_mfma_f32_16x16x32_bf16 v[2:5], v[146:149], v[170:173], v[2:5]
	s_barrier
	s_add_i32 s33, s33, 2
	s_add_u32 s48, s48, 0x100
	s_addc_u32 s49, s49, 0
	s_add_u32 s70, s70, 0x100
	s_addc_u32 s71, s71, 0
	s_cmp_gt_u32 s33, 29
	s_cbranch_scc1 .LBB0_1543
.LBB0_1533:
	v_add_u32_e32 v134, 0x10000, v218
	v_add_u32_e32 v146, 0x14000, v218
	ds_read_b128 v[150:153], v134
	ds_read_b128 v[154:157], v134 offset:1024
	ds_read_b128 v[158:161], v134 offset:2048
	ds_read_b128 v[162:165], v134 offset:3072
	ds_read_b128 v[134:137], v146
	ds_read_b128 v[138:141], v146 offset:1024
	ds_read_b128 v[142:145], v146 offset:2048
	ds_read_b128 v[146:149], v146 offset:3072
	s_add_u32 s52, s48, 0xfff80080
	s_addc_u32 s53, s49, -1
	s_cmp_lg_u32 s33, 28
	s_cselect_b64 s[54:55], -1, 0
	s_and_b64 s[50:51], s[54:55], exec
	s_cselect_b32 s51, s71, s11
	s_cselect_b32 s50, s70, s69
	s_cselect_b32 s53, s53, s13
	s_cselect_b32 s52, s52, s68
	v_lshl_add_u64 v[208:209], s[48:49], 0, v[204:205]
	s_add_i32 m0, s22, 0xc000
	ds_read_b128 v[166:169], v219
	ds_read_b128 v[170:173], v219 offset:1024
	ds_read_b128 v[174:177], v219 offset:2048
	ds_read_b128 v[178:181], v219 offset:3072
	ds_read_b128 v[182:185], v219 offset:4096
	ds_read_b128 v[186:189], v219 offset:5120
	ds_read_b128 v[190:193], v219 offset:6144
	ds_read_b128 v[194:197], v219 offset:7168
	global_load_lds_dwordx4 v[208:209], off
	v_lshl_add_u64 v[208:209], s[48:49], 0, v[206:207]
	s_add_i32 m0, s22, 0xe000
	s_nop 0
	global_load_lds_dwordx4 v[208:209], off
	s_waitcnt vmcnt(8)
	s_waitcnt lgkmcnt(0)
	s_barrier
	s_waitcnt lgkmcnt(0)
	v_mfma_f32_16x16x32_bf16 v[130:133], v[150:153], v[166:169], v[130:133]
	v_mfma_f32_16x16x32_bf16 v[126:129], v[158:161], v[166:169], v[126:129]
	v_mfma_f32_16x16x32_bf16 v[114:117], v[150:153], v[174:177], v[114:117]
	v_mfma_f32_16x16x32_bf16 v[110:113], v[158:161], v[174:177], v[110:113]
	v_mfma_f32_16x16x32_bf16 v[98:101], v[150:153], v[182:185], v[98:101]
	v_mfma_f32_16x16x32_bf16 v[94:97], v[158:161], v[182:185], v[94:97]
	v_mfma_f32_16x16x32_bf16 v[82:85], v[150:153], v[190:193], v[82:85]
	v_mfma_f32_16x16x32_bf16 v[78:81], v[158:161], v[190:193], v[78:81]
	v_mfma_f32_16x16x32_bf16 v[130:133], v[154:157], v[170:173], v[130:133]
	v_mfma_f32_16x16x32_bf16 v[126:129], v[162:165], v[170:173], v[126:129]
	v_mfma_f32_16x16x32_bf16 v[114:117], v[154:157], v[178:181], v[114:117]
	v_mfma_f32_16x16x32_bf16 v[110:113], v[162:165], v[178:181], v[110:113]
	v_mfma_f32_16x16x32_bf16 v[98:101], v[154:157], v[186:189], v[98:101]
	v_mfma_f32_16x16x32_bf16 v[94:97], v[162:165], v[186:189], v[94:97]
	v_mfma_f32_16x16x32_bf16 v[82:85], v[154:157], v[194:197], v[82:85]
	v_mfma_f32_16x16x32_bf16 v[78:81], v[162:165], v[194:197], v[78:81]
	v_mfma_f32_16x16x32_bf16 v[122:125], v[134:137], v[166:169], v[122:125]
	v_mfma_f32_16x16x32_bf16 v[118:121], v[142:145], v[166:169], v[118:121]
	v_mfma_f32_16x16x32_bf16 v[106:109], v[134:137], v[174:177], v[106:109]
	v_mfma_f32_16x16x32_bf16 v[102:105], v[142:145], v[174:177], v[102:105]
	v_mfma_f32_16x16x32_bf16 v[90:93], v[134:137], v[182:185], v[90:93]
	v_mfma_f32_16x16x32_bf16 v[86:89], v[142:145], v[182:185], v[86:89]
	v_mfma_f32_16x16x32_bf16 v[74:77], v[134:137], v[190:193], v[74:77]
	v_mfma_f32_16x16x32_bf16 v[70:73], v[142:145], v[190:193], v[70:73]
	v_mfma_f32_16x16x32_bf16 v[122:125], v[138:141], v[170:173], v[122:125]
	v_mfma_f32_16x16x32_bf16 v[118:121], v[146:149], v[170:173], v[118:121]
	v_mfma_f32_16x16x32_bf16 v[106:109], v[138:141], v[178:181], v[106:109]
	v_mfma_f32_16x16x32_bf16 v[102:105], v[146:149], v[178:181], v[102:105]
	v_mfma_f32_16x16x32_bf16 v[90:93], v[138:141], v[186:189], v[90:93]
	v_mfma_f32_16x16x32_bf16 v[86:89], v[146:149], v[186:189], v[86:89]
	v_mfma_f32_16x16x32_bf16 v[74:77], v[138:141], v[194:197], v[74:77]
	v_mfma_f32_16x16x32_bf16 v[70:73], v[146:149], v[194:197], v[70:73]
	s_barrier
	ds_read_b128 v[190:193], v219 offset:16384
	ds_read_b128 v[194:197], v219 offset:17408
	ds_read_b128 v[182:185], v219 offset:18432
	ds_read_b128 v[186:189], v219 offset:19456
	ds_read_b128 v[174:177], v219 offset:20480
	ds_read_b128 v[178:181], v219 offset:21504
	ds_read_b128 v[166:169], v219 offset:22528
	ds_read_b128 v[170:173], v219 offset:23552
	s_or_b64 s[54:55], s[40:41], s[54:55]
	s_xor_b64 s[56:57], s[54:55], -1
	s_mov_b64 s[58:59], -1
	s_and_b64 vcc, exec, s[56:57]
	s_cbranch_vccz .LBB0_1535
	s_waitcnt vmcnt(2)
	s_mov_b64 s[58:59], 0

.LBB0_1537:
	s_waitcnt lgkmcnt(0)
	s_barrier
	s_waitcnt lgkmcnt(0)
	v_mfma_f32_16x16x32_bf16 v[66:69], v[150:153], v[190:193], v[66:69]
	v_mfma_f32_16x16x32_bf16 v[62:65], v[158:161], v[190:193], v[62:65]
	v_mfma_f32_16x16x32_bf16 v[50:53], v[150:153], v[182:185], v[50:53]
	v_mfma_f32_16x16x32_bf16 v[46:49], v[158:161], v[182:185], v[46:49]
	v_mfma_f32_16x16x32_bf16 v[34:37], v[150:153], v[174:177], v[34:37]
	v_mfma_f32_16x16x32_bf16 v[30:33], v[158:161], v[174:177], v[30:33]
	v_mfma_f32_16x16x32_bf16 v[18:21], v[150:153], v[166:169], v[18:21]
	v_mfma_f32_16x16x32_bf16 v[10:13], v[158:161], v[166:169], v[10:13]
	v_mfma_f32_16x16x32_bf16 v[66:69], v[154:157], v[194:197], v[66:69]
	v_mfma_f32_16x16x32_bf16 v[62:65], v[162:165], v[194:197], v[62:65]
	v_mfma_f32_16x16x32_bf16 v[50:53], v[154:157], v[186:189], v[50:53]
	v_mfma_f32_16x16x32_bf16 v[46:49], v[162:165], v[186:189], v[46:49]
	v_mfma_f32_16x16x32_bf16 v[34:37], v[154:157], v[178:181], v[34:37]
	v_mfma_f32_16x16x32_bf16 v[30:33], v[162:165], v[178:181], v[30:33]
	v_mfma_f32_16x16x32_bf16 v[18:21], v[154:157], v[170:173], v[18:21]
	v_mfma_f32_16x16x32_bf16 v[10:13], v[162:165], v[170:173], v[10:13]
	v_mfma_f32_16x16x32_bf16 v[58:61], v[134:137], v[190:193], v[58:61]
	v_mfma_f32_16x16x32_bf16 v[54:57], v[142:145], v[190:193], v[54:57]
	v_mfma_f32_16x16x32_bf16 v[42:45], v[134:137], v[182:185], v[42:45]
	v_mfma_f32_16x16x32_bf16 v[38:41], v[142:145], v[182:185], v[38:41]
	v_mfma_f32_16x16x32_bf16 v[26:29], v[134:137], v[174:177], v[26:29]
	v_mfma_f32_16x16x32_bf16 v[22:25], v[142:145], v[174:177], v[22:25]
	v_mfma_f32_16x16x32_bf16 v[6:9], v[134:137], v[166:169], v[6:9]
	v_mfma_f32_16x16x32_bf16 v[2:5], v[142:145], v[166:169], v[2:5]
	v_mfma_f32_16x16x32_bf16 v[58:61], v[138:141], v[194:197], v[58:61]
	v_mfma_f32_16x16x32_bf16 v[54:57], v[146:149], v[194:197], v[54:57]
	v_mfma_f32_16x16x32_bf16 v[42:45], v[138:141], v[186:189], v[42:45]
	v_mfma_f32_16x16x32_bf16 v[38:41], v[146:149], v[186:189], v[38:41]
	v_mfma_f32_16x16x32_bf16 v[26:29], v[138:141], v[178:181], v[26:29]
	v_mfma_f32_16x16x32_bf16 v[22:25], v[146:149], v[178:181], v[22:25]
	v_mfma_f32_16x16x32_bf16 v[6:9], v[138:141], v[170:173], v[6:9]
	v_mfma_f32_16x16x32_bf16 v[2:5], v[146:149], v[170:173], v[2:5]
	s_barrier
	v_add_u32_e32 v134, 0x18000, v218
	v_add_u32_e32 v146, 0x1c000, v218
	ds_read_b128 v[150:153], v134
	ds_read_b128 v[154:157], v134 offset:1024
	ds_read_b128 v[158:161], v134 offset:2048
	ds_read_b128 v[162:165], v134 offset:3072
	ds_read_b128 v[134:137], v146
	ds_read_b128 v[138:141], v146 offset:1024
	ds_read_b128 v[142:145], v146 offset:2048
	ds_read_b128 v[146:149], v146 offset:3072
	ds_read_b128 v[190:193], v219 offset:32768
	ds_read_b128 v[194:197], v219 offset:33792
	ds_read_b128 v[182:185], v219 offset:34816
	ds_read_b128 v[186:189], v219 offset:35840
	ds_read_b128 v[174:177], v219 offset:36864
	ds_read_b128 v[178:181], v219 offset:37888
	ds_read_b128 v[166:169], v219 offset:38912
	ds_read_b128 v[170:173], v219 offset:39936
	s_mov_b64 s[58:59], -1
	s_and_b64 vcc, exec, s[56:57]
	s_cbranch_vccz .LBB0_1539
	s_waitcnt vmcnt(0)
	s_mov_b64 s[58:59], 0

.LBB0_1541:
	s_waitcnt lgkmcnt(0)
	s_barrier
	s_waitcnt lgkmcnt(0)
	v_mfma_f32_16x16x32_bf16 v[130:133], v[150:153], v[190:193], v[130:133]
	v_mfma_f32_16x16x32_bf16 v[126:129], v[158:161], v[190:193], v[126:129]
	v_mfma_f32_16x16x32_bf16 v[114:117], v[150:153], v[182:185], v[114:117]
	v_mfma_f32_16x16x32_bf16 v[110:113], v[158:161], v[182:185], v[110:113]
	v_mfma_f32_16x16x32_bf16 v[98:101], v[150:153], v[174:177], v[98:101]
	v_mfma_f32_16x16x32_bf16 v[94:97], v[158:161], v[174:177], v[94:97]
	v_mfma_f32_16x16x32_bf16 v[82:85], v[150:153], v[166:169], v[82:85]
	v_mfma_f32_16x16x32_bf16 v[78:81], v[158:161], v[166:169], v[78:81]
	v_mfma_f32_16x16x32_bf16 v[130:133], v[154:157], v[194:197], v[130:133]
	v_mfma_f32_16x16x32_bf16 v[126:129], v[162:165], v[194:197], v[126:129]
	v_mfma_f32_16x16x32_bf16 v[114:117], v[154:157], v[186:189], v[114:117]
	v_mfma_f32_16x16x32_bf16 v[110:113], v[162:165], v[186:189], v[110:113]
	v_mfma_f32_16x16x32_bf16 v[98:101], v[154:157], v[178:181], v[98:101]
	v_mfma_f32_16x16x32_bf16 v[94:97], v[162:165], v[178:181], v[94:97]
	v_mfma_f32_16x16x32_bf16 v[82:85], v[154:157], v[170:173], v[82:85]
	v_mfma_f32_16x16x32_bf16 v[78:81], v[162:165], v[170:173], v[78:81]
	v_mfma_f32_16x16x32_bf16 v[122:125], v[134:137], v[190:193], v[122:125]
	v_mfma_f32_16x16x32_bf16 v[118:121], v[142:145], v[190:193], v[118:121]
	v_mfma_f32_16x16x32_bf16 v[106:109], v[134:137], v[182:185], v[106:109]
	v_mfma_f32_16x16x32_bf16 v[102:105], v[142:145], v[182:185], v[102:105]
	v_mfma_f32_16x16x32_bf16 v[90:93], v[134:137], v[174:177], v[90:93]
	v_mfma_f32_16x16x32_bf16 v[86:89], v[142:145], v[174:177], v[86:89]
	v_mfma_f32_16x16x32_bf16 v[74:77], v[134:137], v[166:169], v[74:77]
	v_mfma_f32_16x16x32_bf16 v[70:73], v[142:145], v[166:169], v[70:73]
	v_mfma_f32_16x16x32_bf16 v[122:125], v[138:141], v[194:197], v[122:125]
	v_mfma_f32_16x16x32_bf16 v[118:121], v[146:149], v[194:197], v[118:121]
	v_mfma_f32_16x16x32_bf16 v[106:109], v[138:141], v[186:189], v[106:109]
	v_mfma_f32_16x16x32_bf16 v[102:105], v[146:149], v[186:189], v[102:105]
	v_mfma_f32_16x16x32_bf16 v[90:93], v[138:141], v[178:181], v[90:93]
	v_mfma_f32_16x16x32_bf16 v[86:89], v[146:149], v[178:181], v[86:89]
	v_mfma_f32_16x16x32_bf16 v[74:77], v[138:141], v[170:173], v[74:77]
	v_mfma_f32_16x16x32_bf16 v[70:73], v[146:149], v[170:173], v[70:73]
	s_barrier
	ds_read_b128 v[190:193], v219 offset:49152
	ds_read_b128 v[194:197], v219 offset:50176
	ds_read_b128 v[182:185], v219 offset:51200
	ds_read_b128 v[186:189], v219 offset:52224
	ds_read_b128 v[174:177], v219 offset:53248
	ds_read_b128 v[178:181], v219 offset:54272
	ds_read_b128 v[166:169], v219 offset:55296
	ds_read_b128 v[170:173], v219 offset:56320
	s_andn2_b64 vcc, exec, s[54:55]
	s_cbranch_vccnz .LBB0_1532
	s_mov_b32 m0, s47
	v_lshl_add_u64 v[216:217], v[216:217], 0, s[16:17]
	s_add_u32 s50, s50, 0x80080
	global_load_lds_dwordx4 v[216:217], off
	v_lshl_add_u64 v[212:213], v[212:213], 0, s[16:17]
	s_mov_b32 m0, s60
	s_addc_u32 s51, s51, 0
	global_load_lds_dwordx4 v[212:213], off
	v_lshl_add_u64 v[212:213], s[50:51], 0, v[198:199]
	s_mov_b32 m0, s63
	v_lshl_add_u64 v[210:211], v[210:211], 0, s[16:17]
	global_load_lds_dwordx4 v[212:213], off
	v_lshl_add_u64 v[212:213], s[50:51], 0, v[202:203]
	s_mov_b32 m0, s64
	v_lshl_add_u64 v[208:209], v[208:209], 0, s[16:17]
	global_load_lds_dwordx4 v[212:213], off
	s_mov_b32 m0, s61
	s_nop 0
	global_load_lds_dwordx4 v[210:211], off
	s_mov_b32 m0, s62
	s_nop 0
	global_load_lds_dwordx4 v[208:209], off
	s_waitcnt vmcnt(8)
	s_branch .LBB0_1532

.LBB0_1632:
	s_waitcnt lgkmcnt(0)
	s_barrier
	s_waitcnt lgkmcnt(0)
	v_mfma_f32_16x16x32_bf16 v[70:73], v[150:153], v[190:193], v[70:73]
	v_mfma_f32_16x16x32_bf16 v[74:77], v[158:161], v[190:193], v[74:77]
	v_mfma_f32_16x16x32_bf16 v[86:89], v[150:153], v[182:185], v[86:89]
	v_mfma_f32_16x16x32_bf16 v[90:93], v[158:161], v[182:185], v[90:93]
	v_mfma_f32_16x16x32_bf16 v[102:105], v[150:153], v[174:177], v[102:105]
	v_mfma_f32_16x16x32_bf16 v[106:109], v[158:161], v[174:177], v[106:109]
	v_mfma_f32_16x16x32_bf16 v[118:121], v[150:153], v[166:169], v[118:121]
	v_mfma_f32_16x16x32_bf16 v[122:125], v[158:161], v[166:169], v[122:125]
	v_mfma_f32_16x16x32_bf16 v[70:73], v[154:157], v[194:197], v[70:73]
	v_mfma_f32_16x16x32_bf16 v[74:77], v[162:165], v[194:197], v[74:77]
	v_mfma_f32_16x16x32_bf16 v[86:89], v[154:157], v[186:189], v[86:89]
	v_mfma_f32_16x16x32_bf16 v[90:93], v[162:165], v[186:189], v[90:93]
	v_mfma_f32_16x16x32_bf16 v[102:105], v[154:157], v[178:181], v[102:105]
	v_mfma_f32_16x16x32_bf16 v[106:109], v[162:165], v[178:181], v[106:109]
	v_mfma_f32_16x16x32_bf16 v[118:121], v[154:157], v[170:173], v[118:121]
	v_mfma_f32_16x16x32_bf16 v[122:125], v[162:165], v[170:173], v[122:125]
	v_mfma_f32_16x16x32_bf16 v[82:85], v[134:137], v[190:193], v[82:85]
	v_mfma_f32_16x16x32_bf16 v[78:81], v[142:145], v[190:193], v[78:81]
	v_mfma_f32_16x16x32_bf16 v[98:101], v[134:137], v[182:185], v[98:101]
	v_mfma_f32_16x16x32_bf16 v[94:97], v[142:145], v[182:185], v[94:97]
	v_mfma_f32_16x16x32_bf16 v[114:117], v[134:137], v[174:177], v[114:117]
	v_mfma_f32_16x16x32_bf16 v[110:113], v[142:145], v[174:177], v[110:113]
	v_mfma_f32_16x16x32_bf16 v[130:133], v[134:137], v[166:169], v[130:133]
	v_mfma_f32_16x16x32_bf16 v[126:129], v[142:145], v[166:169], v[126:129]
	v_mfma_f32_16x16x32_bf16 v[82:85], v[138:141], v[194:197], v[82:85]
	v_mfma_f32_16x16x32_bf16 v[78:81], v[146:149], v[194:197], v[78:81]
	v_mfma_f32_16x16x32_bf16 v[98:101], v[138:141], v[186:189], v[98:101]
	v_mfma_f32_16x16x32_bf16 v[94:97], v[146:149], v[186:189], v[94:97]
	v_mfma_f32_16x16x32_bf16 v[114:117], v[138:141], v[178:181], v[114:117]
	v_mfma_f32_16x16x32_bf16 v[110:113], v[146:149], v[178:181], v[110:113]
	v_mfma_f32_16x16x32_bf16 v[130:133], v[138:141], v[170:173], v[130:133]
	v_mfma_f32_16x16x32_bf16 v[126:129], v[146:149], v[170:173], v[126:129]
	s_barrier
	s_add_i32 s25, s25, 2
	s_cmpk_gt_u32 s25, 0x7d
	s_cbranch_scc1 .LBB0_1643
.LBB0_1633:
	s_mov_b64 s[10:11], s[66:67]
	s_add_u32 s66, s10, 0x100
	s_addc_u32 s67, s11, 0
	v_add_u32_e32 v0, 0x10000, v250
	s_add_u32 s28, s14, s10
	ds_read_b128 v[150:153], v0
	ds_read_b128 v[154:157], v0 offset:1024
	ds_read_b128 v[158:161], v0 offset:2048
	ds_read_b128 v[162:165], v0 offset:3072
	v_add_u32_e32 v0, 0x14000, v250
	s_addc_u32 s33, s23, s11
	ds_read_b128 v[134:137], v0
	ds_read_b128 v[138:141], v0 offset:1024
	ds_read_b128 v[142:145], v0 offset:2048
	ds_read_b128 v[146:149], v0 offset:3072
	s_cmpk_eq_i32 s25, 0x7c
	s_cselect_b64 s[72:73], -1, 0
	s_and_b64 s[68:69], s[72:73], exec
	s_cselect_b32 s61, 0, s66
	s_cselect_b32 s38, 0, s67
	s_cselect_b32 s71, s0, s33
	s_cselect_b32 s70, s2, s28
	s_add_u32 s68, s48, s61
	s_addc_u32 s69, s49, s38
	v_lshl_add_u64 v[230:231], v[226:227], 0, s[10:11]
	s_add_i32 m0, s47, 0xc000
	ds_read_b128 v[166:169], v251
	ds_read_b128 v[170:173], v251 offset:1024
	ds_read_b128 v[174:177], v251 offset:2048
	ds_read_b128 v[178:181], v251 offset:3072
	ds_read_b128 v[182:185], v251 offset:4096
	ds_read_b128 v[186:189], v251 offset:5120
	ds_read_b128 v[190:193], v251 offset:6144
	ds_read_b128 v[194:197], v251 offset:7168
	global_load_lds_dwordx4 v[230:231], off
	v_lshl_add_u64 v[230:231], v[228:229], 0, s[10:11]
	s_add_i32 m0, s47, 0xe000
	s_nop 0
	global_load_lds_dwordx4 v[230:231], off
	s_waitcnt vmcnt(8)
	s_waitcnt lgkmcnt(0)
	s_barrier
	s_waitcnt lgkmcnt(0)
	v_mfma_f32_16x16x32_bf16 v[22:25], v[150:153], v[166:169], v[22:25]
	v_mfma_f32_16x16x32_bf16 v[26:29], v[158:161], v[166:169], v[26:29]
	v_mfma_f32_16x16x32_bf16 v[18:21], v[150:153], v[174:177], v[18:21]
	v_mfma_f32_16x16x32_bf16 v[10:13], v[158:161], v[174:177], v[10:13]
	v_mfma_f32_16x16x32_bf16 v[30:33], v[150:153], v[182:185], v[30:33]
	v_mfma_f32_16x16x32_bf16 v[34:37], v[158:161], v[182:185], v[34:37]
	v_mfma_f32_16x16x32_bf16 v[54:57], v[150:153], v[190:193], v[54:57]
	v_mfma_f32_16x16x32_bf16 v[58:61], v[158:161], v[190:193], v[58:61]
	v_mfma_f32_16x16x32_bf16 v[22:25], v[154:157], v[170:173], v[22:25]
	v_mfma_f32_16x16x32_bf16 v[26:29], v[162:165], v[170:173], v[26:29]
	v_mfma_f32_16x16x32_bf16 v[18:21], v[154:157], v[178:181], v[18:21]
	v_mfma_f32_16x16x32_bf16 v[10:13], v[162:165], v[178:181], v[10:13]
	v_mfma_f32_16x16x32_bf16 v[30:33], v[154:157], v[186:189], v[30:33]
	v_mfma_f32_16x16x32_bf16 v[34:37], v[162:165], v[186:189], v[34:37]
	v_mfma_f32_16x16x32_bf16 v[54:57], v[154:157], v[194:197], v[54:57]
	v_mfma_f32_16x16x32_bf16 v[58:61], v[162:165], v[194:197], v[58:61]
	v_mfma_f32_16x16x32_bf16 v[50:53], v[134:137], v[166:169], v[50:53]
	v_mfma_f32_16x16x32_bf16 v[46:49], v[142:145], v[166:169], v[46:49]
	v_mfma_f32_16x16x32_bf16 v[6:9], v[134:137], v[174:177], v[6:9]
	v_mfma_f32_16x16x32_bf16 v[2:5], v[142:145], v[174:177], v[2:5]
	v_mfma_f32_16x16x32_bf16 v[42:45], v[134:137], v[182:185], v[42:45]
	v_mfma_f32_16x16x32_bf16 v[38:41], v[142:145], v[182:185], v[38:41]
	v_mfma_f32_16x16x32_bf16 v[66:69], v[134:137], v[190:193], v[66:69]
	v_mfma_f32_16x16x32_bf16 v[62:65], v[142:145], v[190:193], v[62:65]
	v_mfma_f32_16x16x32_bf16 v[50:53], v[138:141], v[170:173], v[50:53]
	v_mfma_f32_16x16x32_bf16 v[46:49], v[146:149], v[170:173], v[46:49]
	v_mfma_f32_16x16x32_bf16 v[6:9], v[138:141], v[178:181], v[6:9]
	v_mfma_f32_16x16x32_bf16 v[2:5], v[146:149], v[178:181], v[2:5]
	v_mfma_f32_16x16x32_bf16 v[42:45], v[138:141], v[186:189], v[42:45]
	v_mfma_f32_16x16x32_bf16 v[38:41], v[146:149], v[186:189], v[38:41]
	v_mfma_f32_16x16x32_bf16 v[66:69], v[138:141], v[194:197], v[66:69]
	v_mfma_f32_16x16x32_bf16 v[62:65], v[146:149], v[194:197], v[62:65]
	s_barrier
	ds_read_b128 v[190:193], v251 offset:16384
	ds_read_b128 v[194:197], v251 offset:17408
	ds_read_b128 v[182:185], v251 offset:18432
	ds_read_b128 v[186:189], v251 offset:19456
	ds_read_b128 v[174:177], v251 offset:20480
	ds_read_b128 v[178:181], v251 offset:21504
	ds_read_b128 v[166:169], v251 offset:22528
	ds_read_b128 v[170:173], v251 offset:23552
	s_and_b64 s[10:11], s[64:65], s[72:73]
	s_mov_b64 s[72:73], -1
	s_and_b64 vcc, exec, s[10:11]
	v_lshl_add_u64 v[236:237], s[68:69], 0, v[200:201]
	v_lshl_add_u64 v[234:235], s[68:69], 0, v[14:15]
	v_lshl_add_u64 v[232:233], s[70:71], 0, v[202:203]
	v_lshl_add_u64 v[230:231], s[70:71], 0, v[198:199]
	s_cbranch_vccnz .LBB0_1635
	s_mov_b32 m0, s82
	s_add_u32 s72, s68, 0x200000
	global_load_lds_dwordx4 v[236:237], off
	s_mov_b32 m0, s83
	s_addc_u32 s73, s69, 0
	global_load_lds_dwordx4 v[234:235], off
	v_lshl_add_u64 v[240:241], s[72:73], 0, v[200:201]
	s_mov_b32 m0, s84
	s_nop 0
	global_load_lds_dwordx4 v[240:241], off
	v_lshl_add_u64 v[240:241], s[72:73], 0, v[14:15]
	s_mov_b32 m0, s85
	s_mov_b64 s[72:73], 0
	global_load_lds_dwordx4 v[240:241], off
	s_mov_b32 m0, s47
	s_nop 0
	global_load_lds_dwordx4 v[232:233], off
	s_mov_b32 m0, s86
	s_nop 0
	global_load_lds_dwordx4 v[230:231], off
	s_waitcnt vmcnt(8)

.LBB0_1637:
	s_waitcnt lgkmcnt(0)
	s_xor_b64 s[72:73], s[10:11], -1
	s_barrier
	s_waitcnt lgkmcnt(0)
	v_mfma_f32_16x16x32_bf16 v[70:73], v[150:153], v[190:193], v[70:73]
	v_mfma_f32_16x16x32_bf16 v[74:77], v[158:161], v[190:193], v[74:77]
	v_mfma_f32_16x16x32_bf16 v[86:89], v[150:153], v[182:185], v[86:89]
	v_mfma_f32_16x16x32_bf16 v[90:93], v[158:161], v[182:185], v[90:93]
	v_mfma_f32_16x16x32_bf16 v[102:105], v[150:153], v[174:177], v[102:105]
	v_mfma_f32_16x16x32_bf16 v[106:109], v[158:161], v[174:177], v[106:109]
	v_mfma_f32_16x16x32_bf16 v[118:121], v[150:153], v[166:169], v[118:121]
	v_mfma_f32_16x16x32_bf16 v[122:125], v[158:161], v[166:169], v[122:125]
	v_mfma_f32_16x16x32_bf16 v[70:73], v[154:157], v[194:197], v[70:73]
	v_mfma_f32_16x16x32_bf16 v[74:77], v[162:165], v[194:197], v[74:77]
	v_mfma_f32_16x16x32_bf16 v[86:89], v[154:157], v[186:189], v[86:89]
	v_mfma_f32_16x16x32_bf16 v[90:93], v[162:165], v[186:189], v[90:93]
	v_mfma_f32_16x16x32_bf16 v[102:105], v[154:157], v[178:181], v[102:105]
	v_mfma_f32_16x16x32_bf16 v[106:109], v[162:165], v[178:181], v[106:109]
	v_mfma_f32_16x16x32_bf16 v[118:121], v[154:157], v[170:173], v[118:121]
	v_mfma_f32_16x16x32_bf16 v[122:125], v[162:165], v[170:173], v[122:125]
	v_mfma_f32_16x16x32_bf16 v[82:85], v[134:137], v[190:193], v[82:85]
	v_mfma_f32_16x16x32_bf16 v[78:81], v[142:145], v[190:193], v[78:81]
	v_mfma_f32_16x16x32_bf16 v[98:101], v[134:137], v[182:185], v[98:101]
	v_mfma_f32_16x16x32_bf16 v[94:97], v[142:145], v[182:185], v[94:97]
	v_mfma_f32_16x16x32_bf16 v[114:117], v[134:137], v[174:177], v[114:117]
	v_mfma_f32_16x16x32_bf16 v[110:113], v[142:145], v[174:177], v[110:113]
	v_mfma_f32_16x16x32_bf16 v[130:133], v[134:137], v[166:169], v[130:133]
	v_mfma_f32_16x16x32_bf16 v[126:129], v[142:145], v[166:169], v[126:129]
	v_mfma_f32_16x16x32_bf16 v[82:85], v[138:141], v[194:197], v[82:85]
	v_mfma_f32_16x16x32_bf16 v[78:81], v[146:149], v[194:197], v[78:81]
	v_mfma_f32_16x16x32_bf16 v[98:101], v[138:141], v[186:189], v[98:101]
	v_mfma_f32_16x16x32_bf16 v[94:97], v[146:149], v[186:189], v[94:97]
	v_mfma_f32_16x16x32_bf16 v[114:117], v[138:141], v[178:181], v[114:117]
	v_mfma_f32_16x16x32_bf16 v[110:113], v[146:149], v[178:181], v[110:113]
	v_mfma_f32_16x16x32_bf16 v[130:133], v[138:141], v[170:173], v[130:133]
	v_mfma_f32_16x16x32_bf16 v[126:129], v[146:149], v[170:173], v[126:129]
	s_barrier
	v_add_u32_e32 v0, 0x18000, v250
	ds_read_b128 v[150:153], v0
	ds_read_b128 v[154:157], v0 offset:1024
	ds_read_b128 v[158:161], v0 offset:2048
	ds_read_b128 v[162:165], v0 offset:3072
	v_add_u32_e32 v0, 0x1c000, v250
	ds_read_b128 v[134:137], v0
	ds_read_b128 v[138:141], v0 offset:1024
	ds_read_b128 v[142:145], v0 offset:2048
	ds_read_b128 v[146:149], v0 offset:3072
	ds_read_b128 v[190:193], v251 offset:32768
	ds_read_b128 v[194:197], v251 offset:33792
	ds_read_b128 v[182:185], v251 offset:34816
	ds_read_b128 v[186:189], v251 offset:35840
	ds_read_b128 v[174:177], v251 offset:36864
	ds_read_b128 v[178:181], v251 offset:37888
	ds_read_b128 v[166:169], v251 offset:38912
	ds_read_b128 v[170:173], v251 offset:39936
	v_cndmask_b32_e64 v0, 0, 1, s[72:73]
	v_cmp_ne_u32_e64 s[10:11], 1, v0
	s_andn2_b64 vcc, exec, s[72:73]
	s_mov_b64 s[72:73], -1
	s_cbranch_vccnz .LBB0_1639
	s_add_u32 s70, s70, 0x200000
	s_addc_u32 s71, s71, 0
	s_mov_b32 m0, s87
	v_lshl_add_u64 v[240:241], s[70:71], 0, v[202:203]
	global_load_lds_dwordx4 v[240:241], off
	v_lshl_add_u64 v[240:241], s[70:71], 0, v[198:199]
	s_mov_b32 m0, s88
	s_mov_b64 s[72:73], 0
	global_load_lds_dwordx4 v[240:241], off
	s_waitcnt vmcnt(8)

.LBB0_1641:
	s_waitcnt lgkmcnt(0)
	s_barrier
	s_waitcnt lgkmcnt(0)
	v_mfma_f32_16x16x32_bf16 v[22:25], v[150:153], v[190:193], v[22:25]
	v_mfma_f32_16x16x32_bf16 v[26:29], v[158:161], v[190:193], v[26:29]
	v_mfma_f32_16x16x32_bf16 v[18:21], v[150:153], v[182:185], v[18:21]
	v_mfma_f32_16x16x32_bf16 v[10:13], v[158:161], v[182:185], v[10:13]
	v_mfma_f32_16x16x32_bf16 v[30:33], v[150:153], v[174:177], v[30:33]
	v_mfma_f32_16x16x32_bf16 v[34:37], v[158:161], v[174:177], v[34:37]
	v_mfma_f32_16x16x32_bf16 v[54:57], v[150:153], v[166:169], v[54:57]
	v_mfma_f32_16x16x32_bf16 v[58:61], v[158:161], v[166:169], v[58:61]
	v_mfma_f32_16x16x32_bf16 v[22:25], v[154:157], v[194:197], v[22:25]
	v_mfma_f32_16x16x32_bf16 v[26:29], v[162:165], v[194:197], v[26:29]
	v_mfma_f32_16x16x32_bf16 v[18:21], v[154:157], v[186:189], v[18:21]
	v_mfma_f32_16x16x32_bf16 v[10:13], v[162:165], v[186:189], v[10:13]
	v_mfma_f32_16x16x32_bf16 v[30:33], v[154:157], v[178:181], v[30:33]
	v_mfma_f32_16x16x32_bf16 v[34:37], v[162:165], v[178:181], v[34:37]
	v_mfma_f32_16x16x32_bf16 v[54:57], v[154:157], v[170:173], v[54:57]
	v_mfma_f32_16x16x32_bf16 v[58:61], v[162:165], v[170:173], v[58:61]
	v_mfma_f32_16x16x32_bf16 v[50:53], v[134:137], v[190:193], v[50:53]
	v_mfma_f32_16x16x32_bf16 v[46:49], v[142:145], v[190:193], v[46:49]
	v_mfma_f32_16x16x32_bf16 v[6:9], v[134:137], v[182:185], v[6:9]
	v_mfma_f32_16x16x32_bf16 v[2:5], v[142:145], v[182:185], v[2:5]
	v_mfma_f32_16x16x32_bf16 v[42:45], v[134:137], v[174:177], v[42:45]
	v_mfma_f32_16x16x32_bf16 v[38:41], v[142:145], v[174:177], v[38:41]
	v_mfma_f32_16x16x32_bf16 v[66:69], v[134:137], v[166:169], v[66:69]
	v_mfma_f32_16x16x32_bf16 v[62:65], v[142:145], v[166:169], v[62:65]
	v_mfma_f32_16x16x32_bf16 v[50:53], v[138:141], v[194:197], v[50:53]
	v_mfma_f32_16x16x32_bf16 v[46:49], v[146:149], v[194:197], v[46:49]
	v_mfma_f32_16x16x32_bf16 v[6:9], v[138:141], v[186:189], v[6:9]
	v_mfma_f32_16x16x32_bf16 v[2:5], v[146:149], v[186:189], v[2:5]
	v_mfma_f32_16x16x32_bf16 v[42:45], v[138:141], v[178:181], v[42:45]
	v_mfma_f32_16x16x32_bf16 v[38:41], v[146:149], v[178:181], v[38:41]
	v_mfma_f32_16x16x32_bf16 v[66:69], v[138:141], v[170:173], v[66:69]
	v_mfma_f32_16x16x32_bf16 v[62:65], v[146:149], v[170:173], v[62:65]
	s_barrier
	ds_read_b128 v[190:193], v251 offset:49152
	ds_read_b128 v[194:197], v251 offset:50176
	ds_read_b128 v[182:185], v251 offset:51200
	ds_read_b128 v[186:189], v251 offset:52224
	ds_read_b128 v[174:177], v251 offset:53248
	ds_read_b128 v[178:181], v251 offset:54272
	ds_read_b128 v[166:169], v251 offset:55296
	ds_read_b128 v[170:173], v251 offset:56320
	s_and_b64 vcc, exec, s[10:11]
	s_cbranch_vccnz .LBB0_1632
	s_mov_b32 m0, s91
	v_lshl_add_u64 v[236:237], v[236:237], 0, s[16:17]
	s_add_u32 s10, s68, 0x200080
	global_load_lds_dwordx4 v[236:237], off
	v_lshl_add_u64 v[234:235], v[234:235], 0, s[16:17]
	s_mov_b32 m0, s92
	s_addc_u32 s11, s69, 0
	global_load_lds_dwordx4 v[234:235], off
	v_lshl_add_u64 v[234:235], s[10:11], 0, v[200:201]
	s_mov_b32 m0, s3
	v_lshl_add_u64 v[232:233], v[232:233], 0, s[16:17]
	global_load_lds_dwordx4 v[234:235], off
	v_lshl_add_u64 v[234:235], s[10:11], 0, v[14:15]
	s_mov_b32 m0, s95
	v_lshl_add_u64 v[230:231], v[230:231], 0, s[16:17]
	global_load_lds_dwordx4 v[234:235], off
	s_mov_b32 m0, s93
	s_nop 0
	global_load_lds_dwordx4 v[232:233], off
	s_mov_b32 m0, s94
	s_nop 0
	global_load_lds_dwordx4 v[230:231], off
	s_waitcnt vmcnt(8)
	s_branch .LBB0_1632

.LBB0_1717:
	s_waitcnt lgkmcnt(0)
	s_barrier
	s_waitcnt lgkmcnt(0)
	v_mfma_f32_16x16x32_bf16 v[66:69], v[158:161], v[190:193], v[66:69]
	v_mfma_f32_16x16x32_bf16 v[62:65], v[166:169], v[190:193], v[62:65]
	v_mfma_f32_16x16x32_bf16 v[50:53], v[158:161], v[182:185], v[50:53]
	v_mfma_f32_16x16x32_bf16 v[46:49], v[166:169], v[182:185], v[46:49]
	v_mfma_f32_16x16x32_bf16 v[34:37], v[158:161], v[174:177], v[34:37]
	v_mfma_f32_16x16x32_bf16 v[30:33], v[166:169], v[174:177], v[30:33]
	v_mfma_f32_16x16x32_bf16 v[18:21], v[158:161], v[126:129], v[18:21]
	v_mfma_f32_16x16x32_bf16 v[10:13], v[166:169], v[126:129], v[10:13]
	v_mfma_f32_16x16x32_bf16 v[66:69], v[162:165], v[194:197], v[66:69]
	v_mfma_f32_16x16x32_bf16 v[62:65], v[170:173], v[194:197], v[62:65]
	v_mfma_f32_16x16x32_bf16 v[50:53], v[162:165], v[186:189], v[50:53]
	v_mfma_f32_16x16x32_bf16 v[46:49], v[170:173], v[186:189], v[46:49]
	v_mfma_f32_16x16x32_bf16 v[34:37], v[162:165], v[178:181], v[34:37]
	v_mfma_f32_16x16x32_bf16 v[30:33], v[170:173], v[178:181], v[30:33]
	v_mfma_f32_16x16x32_bf16 v[18:21], v[162:165], v[130:133], v[18:21]
	v_mfma_f32_16x16x32_bf16 v[10:13], v[170:173], v[130:133], v[10:13]
	v_mfma_f32_16x16x32_bf16 v[58:61], v[134:137], v[190:193], v[58:61]
	v_mfma_f32_16x16x32_bf16 v[54:57], v[150:153], v[190:193], v[54:57]
	v_mfma_f32_16x16x32_bf16 v[42:45], v[134:137], v[182:185], v[42:45]
	v_mfma_f32_16x16x32_bf16 v[38:41], v[150:153], v[182:185], v[38:41]
	v_mfma_f32_16x16x32_bf16 v[26:29], v[134:137], v[174:177], v[26:29]
	v_mfma_f32_16x16x32_bf16 v[22:25], v[150:153], v[174:177], v[22:25]
	v_mfma_f32_16x16x32_bf16 v[6:9], v[134:137], v[126:129], v[6:9]
	v_mfma_f32_16x16x32_bf16 v[2:5], v[150:153], v[126:129], v[2:5]
	v_mfma_f32_16x16x32_bf16 v[58:61], v[138:141], v[194:197], v[58:61]
	v_mfma_f32_16x16x32_bf16 v[54:57], v[154:157], v[194:197], v[54:57]
	v_mfma_f32_16x16x32_bf16 v[42:45], v[138:141], v[186:189], v[42:45]
	v_mfma_f32_16x16x32_bf16 v[38:41], v[154:157], v[186:189], v[38:41]
	v_mfma_f32_16x16x32_bf16 v[26:29], v[138:141], v[178:181], v[26:29]
	v_mfma_f32_16x16x32_bf16 v[22:25], v[154:157], v[178:181], v[22:25]
	v_mfma_f32_16x16x32_bf16 v[6:9], v[138:141], v[130:133], v[6:9]
	v_mfma_f32_16x16x32_bf16 v[2:5], v[154:157], v[130:133], v[2:5]
	s_barrier
	s_add_i32 s33, s33, 2
	s_add_u32 s50, s50, 0x100
	s_addc_u32 s51, s51, 0
	s_add_u32 s69, s69, 0x100
	s_addc_u32 s70, s70, 0
	s_cmpk_gt_u32 s33, 0x7d
	s_cbranch_scc1 .LBB0_1728
.LBB0_1718:
	v_add_u32_e32 v126, 0x10000, v226
	ds_read_b128 v[158:161], v126
	ds_read_b128 v[162:165], v126 offset:1024
	ds_read_b128 v[166:169], v126 offset:2048
	ds_read_b128 v[170:173], v126 offset:3072
	v_add_u32_e32 v126, 0x14000, v226
	ds_read_b128 v[134:137], v126
	ds_read_b128 v[138:141], v126 offset:1024
	ds_read_b128 v[150:153], v126 offset:2048
	ds_read_b128 v[154:157], v126 offset:3072
	s_add_u32 s54, s50, 0xffe00080
	s_addc_u32 s55, s51, -1
	s_cmpk_lg_i32 s33, 0x7c
	s_cselect_b64 s[56:57], -1, 0
	s_and_b64 s[52:53], s[56:57], exec
	s_cselect_b32 s53, s70, s13
	s_cselect_b32 s52, s69, s68
	s_cselect_b32 s55, s55, s41
	s_cselect_b32 s54, s54, s67
	v_lshl_add_u64 v[126:127], s[50:51], 0, v[212:213]
	s_add_i32 m0, s1, 0xc000
	ds_read_b128 v[174:177], v227
	ds_read_b128 v[178:181], v227 offset:1024
	ds_read_b128 v[182:185], v227 offset:2048
	ds_read_b128 v[186:189], v227 offset:3072
	ds_read_b128 v[190:193], v227 offset:4096
	ds_read_b128 v[194:197], v227 offset:5120
	ds_read_b128 v[198:201], v227 offset:6144
	ds_read_b128 v[202:205], v227 offset:7168
	global_load_lds_dwordx4 v[126:127], off
	v_lshl_add_u64 v[126:127], s[50:51], 0, v[216:217]
	s_add_i32 m0, s1, 0xe000
	s_nop 0
	global_load_lds_dwordx4 v[126:127], off
	s_waitcnt vmcnt(8)
	s_waitcnt lgkmcnt(0)
	s_barrier
	s_waitcnt lgkmcnt(0)
	v_mfma_f32_16x16x32_bf16 v[126:129], v[158:161], v[174:177], v[146:149]
	v_mfma_f32_16x16x32_bf16 v[130:133], v[166:169], v[174:177], v[142:145]
	v_mfma_f32_16x16x32_bf16 v[114:117], v[158:161], v[182:185], v[114:117]
	v_mfma_f32_16x16x32_bf16 v[110:113], v[166:169], v[182:185], v[110:113]
	v_mfma_f32_16x16x32_bf16 v[98:101], v[158:161], v[190:193], v[98:101]
	v_mfma_f32_16x16x32_bf16 v[94:97], v[166:169], v[190:193], v[94:97]
	v_mfma_f32_16x16x32_bf16 v[82:85], v[158:161], v[198:201], v[82:85]
	v_mfma_f32_16x16x32_bf16 v[78:81], v[166:169], v[198:201], v[78:81]
	v_mfma_f32_16x16x32_bf16 v[126:129], v[162:165], v[178:181], v[126:129]
	v_mfma_f32_16x16x32_bf16 v[130:133], v[170:173], v[178:181], v[130:133]
	v_mfma_f32_16x16x32_bf16 v[114:117], v[162:165], v[186:189], v[114:117]
	v_mfma_f32_16x16x32_bf16 v[110:113], v[170:173], v[186:189], v[110:113]
	v_mfma_f32_16x16x32_bf16 v[98:101], v[162:165], v[194:197], v[98:101]
	v_mfma_f32_16x16x32_bf16 v[94:97], v[170:173], v[194:197], v[94:97]
	v_mfma_f32_16x16x32_bf16 v[82:85], v[162:165], v[202:205], v[82:85]
	v_mfma_f32_16x16x32_bf16 v[78:81], v[170:173], v[202:205], v[78:81]
	v_mfma_f32_16x16x32_bf16 v[122:125], v[134:137], v[174:177], v[122:125]
	v_mfma_f32_16x16x32_bf16 v[118:121], v[150:153], v[174:177], v[118:121]
	v_mfma_f32_16x16x32_bf16 v[106:109], v[134:137], v[182:185], v[106:109]
	v_mfma_f32_16x16x32_bf16 v[102:105], v[150:153], v[182:185], v[102:105]
	v_mfma_f32_16x16x32_bf16 v[90:93], v[134:137], v[190:193], v[90:93]
	v_mfma_f32_16x16x32_bf16 v[86:89], v[150:153], v[190:193], v[86:89]
	v_mfma_f32_16x16x32_bf16 v[74:77], v[134:137], v[198:201], v[74:77]
	v_mfma_f32_16x16x32_bf16 v[70:73], v[150:153], v[198:201], v[70:73]
	v_mfma_f32_16x16x32_bf16 v[122:125], v[138:141], v[178:181], v[122:125]
	v_mfma_f32_16x16x32_bf16 v[118:121], v[154:157], v[178:181], v[118:121]
	v_mfma_f32_16x16x32_bf16 v[106:109], v[138:141], v[186:189], v[106:109]
	v_mfma_f32_16x16x32_bf16 v[102:105], v[154:157], v[186:189], v[102:105]
	v_mfma_f32_16x16x32_bf16 v[90:93], v[138:141], v[194:197], v[90:93]
	v_mfma_f32_16x16x32_bf16 v[86:89], v[154:157], v[194:197], v[86:89]
	v_mfma_f32_16x16x32_bf16 v[74:77], v[138:141], v[202:205], v[74:77]
	v_mfma_f32_16x16x32_bf16 v[70:73], v[154:157], v[202:205], v[70:73]
	s_barrier
	ds_read_b128 v[190:193], v227 offset:16384
	ds_read_b128 v[194:197], v227 offset:17408
	ds_read_b128 v[182:185], v227 offset:18432
	ds_read_b128 v[186:189], v227 offset:19456
	ds_read_b128 v[174:177], v227 offset:20480
	ds_read_b128 v[178:181], v227 offset:21504
	ds_read_b128 v[142:145], v227 offset:22528
	ds_read_b128 v[146:149], v227 offset:23552
	s_or_b64 s[56:57], s[42:43], s[56:57]
	s_xor_b64 s[58:59], s[56:57], -1
	s_mov_b64 s[60:61], -1
	s_and_b64 vcc, exec, s[58:59]
	s_cbranch_vccz .LBB0_1720
	s_waitcnt vmcnt(2)
	s_mov_b64 s[60:61], 0

.LBB0_1722:
	s_waitcnt lgkmcnt(0)
	s_barrier
	s_waitcnt lgkmcnt(0)
	v_mfma_f32_16x16x32_bf16 v[66:69], v[158:161], v[190:193], v[66:69]
	v_mfma_f32_16x16x32_bf16 v[62:65], v[166:169], v[190:193], v[62:65]
	v_mfma_f32_16x16x32_bf16 v[50:53], v[158:161], v[182:185], v[50:53]
	v_mfma_f32_16x16x32_bf16 v[46:49], v[166:169], v[182:185], v[46:49]
	v_mfma_f32_16x16x32_bf16 v[34:37], v[158:161], v[174:177], v[34:37]
	v_mfma_f32_16x16x32_bf16 v[30:33], v[166:169], v[174:177], v[30:33]
	v_mfma_f32_16x16x32_bf16 v[18:21], v[158:161], v[142:145], v[18:21]
	v_mfma_f32_16x16x32_bf16 v[10:13], v[166:169], v[142:145], v[10:13]
	v_mfma_f32_16x16x32_bf16 v[66:69], v[162:165], v[194:197], v[66:69]
	v_mfma_f32_16x16x32_bf16 v[62:65], v[170:173], v[194:197], v[62:65]
	v_mfma_f32_16x16x32_bf16 v[50:53], v[162:165], v[186:189], v[50:53]
	v_mfma_f32_16x16x32_bf16 v[46:49], v[170:173], v[186:189], v[46:49]
	v_mfma_f32_16x16x32_bf16 v[34:37], v[162:165], v[178:181], v[34:37]
	v_mfma_f32_16x16x32_bf16 v[30:33], v[170:173], v[178:181], v[30:33]
	v_mfma_f32_16x16x32_bf16 v[18:21], v[162:165], v[146:149], v[18:21]
	v_mfma_f32_16x16x32_bf16 v[10:13], v[170:173], v[146:149], v[10:13]
	v_mfma_f32_16x16x32_bf16 v[58:61], v[134:137], v[190:193], v[58:61]
	v_mfma_f32_16x16x32_bf16 v[54:57], v[150:153], v[190:193], v[54:57]
	v_mfma_f32_16x16x32_bf16 v[42:45], v[134:137], v[182:185], v[42:45]
	v_mfma_f32_16x16x32_bf16 v[38:41], v[150:153], v[182:185], v[38:41]
	v_mfma_f32_16x16x32_bf16 v[26:29], v[134:137], v[174:177], v[26:29]
	v_mfma_f32_16x16x32_bf16 v[22:25], v[150:153], v[174:177], v[22:25]
	v_mfma_f32_16x16x32_bf16 v[6:9], v[134:137], v[142:145], v[6:9]
	v_mfma_f32_16x16x32_bf16 v[2:5], v[150:153], v[142:145], v[2:5]
	v_mfma_f32_16x16x32_bf16 v[58:61], v[138:141], v[194:197], v[58:61]
	v_mfma_f32_16x16x32_bf16 v[54:57], v[154:157], v[194:197], v[54:57]
	v_mfma_f32_16x16x32_bf16 v[42:45], v[138:141], v[186:189], v[42:45]
	v_mfma_f32_16x16x32_bf16 v[38:41], v[154:157], v[186:189], v[38:41]
	v_mfma_f32_16x16x32_bf16 v[26:29], v[138:141], v[178:181], v[26:29]
	v_mfma_f32_16x16x32_bf16 v[22:25], v[154:157], v[178:181], v[22:25]
	v_mfma_f32_16x16x32_bf16 v[6:9], v[138:141], v[146:149], v[6:9]
	v_mfma_f32_16x16x32_bf16 v[2:5], v[154:157], v[146:149], v[2:5]
	s_barrier
	v_add_u32_e32 v134, 0x18000, v226
	v_add_u32_e32 v142, 0x1c000, v226
	ds_read_b128 v[158:161], v134
	ds_read_b128 v[162:165], v134 offset:1024
	ds_read_b128 v[166:169], v134 offset:2048
	ds_read_b128 v[170:173], v134 offset:3072
	ds_read_b128 v[134:137], v142
	ds_read_b128 v[138:141], v142 offset:1024
	ds_read_b128 v[150:153], v142 offset:2048
	ds_read_b128 v[154:157], v142 offset:3072
	ds_read_b128 v[198:201], v227 offset:32768
	ds_read_b128 v[202:205], v227 offset:33792
	ds_read_b128 v[190:193], v227 offset:34816
	ds_read_b128 v[194:197], v227 offset:35840
	ds_read_b128 v[182:185], v227 offset:36864
	ds_read_b128 v[186:189], v227 offset:37888
	ds_read_b128 v[174:177], v227 offset:38912
	ds_read_b128 v[178:181], v227 offset:39936
	s_mov_b64 s[60:61], -1
	s_and_b64 vcc, exec, s[58:59]
	s_cbranch_vccz .LBB0_1724
	s_waitcnt vmcnt(0)
	s_mov_b64 s[60:61], 0

.LBB0_1726:
	s_waitcnt lgkmcnt(0)
	s_barrier
	s_waitcnt lgkmcnt(0)
	v_mfma_f32_16x16x32_bf16 v[126:129], v[158:161], v[198:201], v[126:129]
	v_mfma_f32_16x16x32_bf16 v[146:149], v[162:165], v[202:205], v[126:129]
	v_mfma_f32_16x16x32_bf16 v[126:129], v[166:169], v[198:201], v[130:133]
	v_mfma_f32_16x16x32_bf16 v[114:117], v[158:161], v[190:193], v[114:117]
	v_mfma_f32_16x16x32_bf16 v[110:113], v[166:169], v[190:193], v[110:113]
	v_mfma_f32_16x16x32_bf16 v[98:101], v[158:161], v[182:185], v[98:101]
	v_mfma_f32_16x16x32_bf16 v[94:97], v[166:169], v[182:185], v[94:97]
	v_mfma_f32_16x16x32_bf16 v[82:85], v[158:161], v[174:177], v[82:85]
	v_mfma_f32_16x16x32_bf16 v[78:81], v[166:169], v[174:177], v[78:81]
	v_mfma_f32_16x16x32_bf16 v[142:145], v[170:173], v[202:205], v[126:129]
	v_mfma_f32_16x16x32_bf16 v[114:117], v[162:165], v[194:197], v[114:117]
	v_mfma_f32_16x16x32_bf16 v[110:113], v[170:173], v[194:197], v[110:113]
	v_mfma_f32_16x16x32_bf16 v[98:101], v[162:165], v[186:189], v[98:101]
	v_mfma_f32_16x16x32_bf16 v[94:97], v[170:173], v[186:189], v[94:97]
	v_mfma_f32_16x16x32_bf16 v[82:85], v[162:165], v[178:181], v[82:85]
	v_mfma_f32_16x16x32_bf16 v[78:81], v[170:173], v[178:181], v[78:81]
	v_mfma_f32_16x16x32_bf16 v[122:125], v[134:137], v[198:201], v[122:125]
	v_mfma_f32_16x16x32_bf16 v[118:121], v[150:153], v[198:201], v[118:121]
	v_mfma_f32_16x16x32_bf16 v[106:109], v[134:137], v[190:193], v[106:109]
	v_mfma_f32_16x16x32_bf16 v[102:105], v[150:153], v[190:193], v[102:105]
	v_mfma_f32_16x16x32_bf16 v[90:93], v[134:137], v[182:185], v[90:93]
	v_mfma_f32_16x16x32_bf16 v[86:89], v[150:153], v[182:185], v[86:89]
	v_mfma_f32_16x16x32_bf16 v[74:77], v[134:137], v[174:177], v[74:77]
	v_mfma_f32_16x16x32_bf16 v[70:73], v[150:153], v[174:177], v[70:73]
	v_mfma_f32_16x16x32_bf16 v[122:125], v[138:141], v[202:205], v[122:125]
	v_mfma_f32_16x16x32_bf16 v[118:121], v[154:157], v[202:205], v[118:121]
	v_mfma_f32_16x16x32_bf16 v[106:109], v[138:141], v[194:197], v[106:109]
	v_mfma_f32_16x16x32_bf16 v[102:105], v[154:157], v[194:197], v[102:105]
	v_mfma_f32_16x16x32_bf16 v[90:93], v[138:141], v[186:189], v[90:93]
	v_mfma_f32_16x16x32_bf16 v[86:89], v[154:157], v[186:189], v[86:89]
	v_mfma_f32_16x16x32_bf16 v[74:77], v[138:141], v[178:181], v[74:77]
	v_mfma_f32_16x16x32_bf16 v[70:73], v[154:157], v[178:181], v[70:73]
	s_barrier
	ds_read_b128 v[190:193], v227 offset:49152
	ds_read_b128 v[194:197], v227 offset:50176
	ds_read_b128 v[182:185], v227 offset:51200
	ds_read_b128 v[186:189], v227 offset:52224
	ds_read_b128 v[174:177], v227 offset:53248
	ds_read_b128 v[178:181], v227 offset:54272
	ds_read_b128 v[126:129], v227 offset:55296
	ds_read_b128 v[130:133], v227 offset:56320
	s_andn2_b64 vcc, exec, s[56:57]
	s_cbranch_vccnz .LBB0_1717
	s_mov_b32 m0, s29
	v_lshl_add_u64 v[198:199], v[224:225], 0, s[16:17]
	s_add_u32 s52, s52, 0x200080
	global_load_lds_dwordx4 v[198:199], off
	v_lshl_add_u64 v[198:199], v[222:223], 0, s[16:17]
	s_mov_b32 m0, s36
	s_addc_u32 s53, s53, 0
	global_load_lds_dwordx4 v[198:199], off
	v_lshl_add_u64 v[198:199], s[52:53], 0, v[206:207]
	s_mov_b32 m0, s62
	s_nop 0
	global_load_lds_dwordx4 v[198:199], off
	v_lshl_add_u64 v[198:199], s[52:53], 0, v[210:211]
	s_mov_b32 m0, s63
	s_nop 0
	global_load_lds_dwordx4 v[198:199], off
	v_lshl_add_u64 v[198:199], v[220:221], 0, s[16:17]
	s_mov_b32 m0, s38
	s_nop 0
	global_load_lds_dwordx4 v[198:199], off
	v_lshl_add_u64 v[198:199], v[218:219], 0, s[16:17]
	s_mov_b32 m0, s49
	s_nop 0
	global_load_lds_dwordx4 v[198:199], off
	s_waitcnt vmcnt(8)
	s_branch .LBB0_1717
